# grid barrier: every workgroup starts an L2 writeback (buffer_wbl2 sc1, not waited) on arrival so the XCD leader's flush has less dirty data
# baseline (speedup 1.0000x reference)
.LBB0_149:
	s_cmp_gt_i32 s67, 1
	s_cbranch_scc0 .LBB0_203
	s_waitcnt vmcnt(0)
	v_readlane_b32 s4, v232, 0
	v_readlane_b32 s5, v232, 1
	s_waitcnt lgkmcnt(0)
	s_barrier
	s_and_saveexec_b64 s[6:7], s[4:5]
	s_cbranch_execz .LBB0_202
	s_add_i32 s3, 0, 0x20000
	v_mov_b32_e32 v0, s3
	s_waitcnt vmcnt(0) expcnt(0) lgkmcnt(0)
	buffer_wbl2 sc1
	ds_read_b32 v2, v0
	s_add_i32 s3, 0, 0x20004
	v_mov_b32_e32 v0, s3
	ds_read_b32 v0, v0
	s_waitcnt lgkmcnt(1)
	v_cmp_ne_u32_e32 vcc, 0, v2
	s_cbranch_vccnz .LBB0_166
	s_add_u32 s8, s68, 0x23718200
	s_addc_u32 s9, s69, 0
	s_add_u32 s10, s68, 0x23718400
	s_addc_u32 s11, s69, 0
	s_add_u32 s12, s68, 0x23718500
	s_addc_u32 s13, s69, 0
	s_add_u32 s14, s68, 0x23718600
	s_addc_u32 s15, s69, 0
	s_add_u32 s16, s68, 0x23718700
	s_addc_u32 s17, s69, 0
	s_add_u32 s18, s68, 0x23718800
	s_addc_u32 s19, s69, 0
	s_add_u32 s20, s68, 0x23718900
	s_addc_u32 s21, s69, 0
	s_add_u32 s22, s68, 0x23718a00
	s_addc_u32 s23, s69, 0
	s_add_u32 s24, s68, 0x23718b00
	s_addc_u32 s25, s69, 0
	s_add_u32 s26, s68, 0x23718c00
	s_addc_u32 s27, s69, 0
	s_add_u32 s28, s68, 0x23718d00
	s_addc_u32 s29, s69, 0
	s_add_u32 s30, s68, 0x23718e00
	s_addc_u32 s31, s69, 0
	s_add_u32 s34, s68, 0x23718f00
	s_addc_u32 s35, s69, 0
	s_add_u32 s36, s68, 0x23719000
	s_load_dword s3, s[0:1], 0x110
	s_addc_u32 s37, s69, 0
	s_add_u32 s38, s68, 0x23719100
	s_addc_u32 s39, s69, 0
	s_add_u32 s40, s68, 0x23719200
	s_addc_u32 s41, s69, 0
	s_waitcnt lgkmcnt(0)
	s_mul_i32 s3, s65, s3
	s_add_u32 s42, s68, 0x23719300
	s_mul_i32 s3, s3, s64
	s_addc_u32 s43, s69, 0
	s_mov_b32 s50, 1
	v_mov_b32_e32 v16, 0
	s_branch .LBB0_154

.LBB0_209:
	s_or_b64 exec, exec, s[6:7]
	s_cmp_lt_i32 s67, 3
	s_cbranch_scc1 .LBB0_263
	s_waitcnt vmcnt(0)
	v_readlane_b32 s4, v232, 0
	v_readlane_b32 s5, v232, 1
	s_barrier
	s_and_saveexec_b64 s[6:7], s[4:5]
	s_cbranch_execz .LBB0_262
	s_add_i32 s8, 0, 0x20000
	v_mov_b32_e32 v0, s8
	s_waitcnt vmcnt(0) expcnt(0) lgkmcnt(0)
	buffer_wbl2 sc1
	ds_read_b32 v2, v0
	s_add_i32 s8, 0, 0x20004
	v_mov_b32_e32 v0, s8
	ds_read_b32 v0, v0
	s_waitcnt lgkmcnt(1)
	v_cmp_ne_u32_e32 vcc, 0, v2
	s_cbranch_vccnz .LBB0_226
	s_load_dword s4, s[0:1], 0x110
	s_mov_b32 s50, 1
	v_mov_b32_e32 v16, 0
	s_waitcnt lgkmcnt(0)
	s_mul_i32 s8, s65, s4
	s_mul_i32 s3, s8, s3
	s_add_u32 s8, s68, 0x23718200
	s_addc_u32 s9, s69, 0
	s_add_u32 s10, s68, 0x23718400
	s_addc_u32 s11, s69, 0
	s_add_u32 s12, s68, 0x23718500
	s_addc_u32 s13, s69, 0
	s_add_u32 s14, s68, 0x23718600
	s_addc_u32 s15, s69, 0
	s_add_u32 s16, s68, 0x23718700
	s_addc_u32 s17, s69, 0
	s_add_u32 s18, s68, 0x23718800
	s_addc_u32 s19, s69, 0
	s_add_u32 s20, s68, 0x23718900
	s_addc_u32 s21, s69, 0
	s_add_u32 s22, s68, 0x23718a00
	s_addc_u32 s23, s69, 0
	s_add_u32 s24, s68, 0x23718b00
	s_addc_u32 s25, s69, 0
	s_add_u32 s26, s68, 0x23718c00
	s_addc_u32 s27, s69, 0
	s_add_u32 s28, s68, 0x23718d00
	s_addc_u32 s29, s69, 0
	s_add_u32 s30, s68, 0x23718e00
	s_addc_u32 s31, s69, 0
	s_add_u32 s34, s68, 0x23718f00
	s_addc_u32 s35, s69, 0
	s_add_u32 s36, s68, 0x23719000
	s_addc_u32 s37, s69, 0
	s_add_u32 s38, s68, 0x23719100
	s_addc_u32 s39, s69, 0
	s_add_u32 s40, s68, 0x23719200
	s_addc_u32 s41, s69, 0
	s_add_u32 s42, s68, 0x23719300
	s_addc_u32 s43, s69, 0
	s_branch .LBB0_214

.LBB0_284:
	s_cmp_lt_i32 s67, 4
	s_cbranch_scc1 .LBB0_338
	s_waitcnt vmcnt(0)
	v_readlane_b32 s4, v232, 0
	v_readlane_b32 s5, v232, 1
	s_waitcnt vmcnt(0)
	s_barrier
	s_and_saveexec_b64 s[6:7], s[4:5]
	s_cbranch_execz .LBB0_337
	s_add_i32 s8, 0, 0x20000
	v_mov_b32_e32 v0, s8
	s_waitcnt vmcnt(0) expcnt(0) lgkmcnt(0)
	buffer_wbl2 sc1
	ds_read_b32 v2, v0
	s_add_i32 s8, 0, 0x20004
	v_mov_b32_e32 v0, s8
	ds_read_b32 v0, v0
	s_waitcnt lgkmcnt(1)
	v_cmp_ne_u32_e32 vcc, 0, v2
	s_cbranch_vccnz .LBB0_301
	s_load_dword s4, s[0:1], 0x110
	s_mov_b32 s50, 1
	v_mov_b32_e32 v16, 0
	s_waitcnt lgkmcnt(0)
	s_mul_i32 s8, s65, s4
	s_mul_i32 s3, s8, s3
	s_add_u32 s8, s68, 0x23718200
	s_addc_u32 s9, s69, 0
	s_add_u32 s10, s68, 0x23718400
	s_addc_u32 s11, s69, 0
	s_add_u32 s12, s68, 0x23718500
	s_addc_u32 s13, s69, 0
	s_add_u32 s14, s68, 0x23718600
	s_addc_u32 s15, s69, 0
	s_add_u32 s16, s68, 0x23718700
	s_addc_u32 s17, s69, 0
	s_add_u32 s18, s68, 0x23718800
	s_addc_u32 s19, s69, 0
	s_add_u32 s20, s68, 0x23718900
	s_addc_u32 s21, s69, 0
	s_add_u32 s22, s68, 0x23718a00
	s_addc_u32 s23, s69, 0
	s_add_u32 s24, s68, 0x23718b00
	s_addc_u32 s25, s69, 0
	s_add_u32 s26, s68, 0x23718c00
	s_addc_u32 s27, s69, 0
	s_add_u32 s28, s68, 0x23718d00
	s_addc_u32 s29, s69, 0
	s_add_u32 s30, s68, 0x23718e00
	s_addc_u32 s31, s69, 0
	s_add_u32 s34, s68, 0x23718f00
	s_addc_u32 s35, s69, 0
	s_add_u32 s36, s68, 0x23719000
	s_addc_u32 s37, s69, 0
	s_add_u32 s38, s68, 0x23719100
	s_addc_u32 s39, s69, 0
	s_add_u32 s40, s68, 0x23719200
	s_addc_u32 s41, s69, 0
	s_add_u32 s42, s68, 0x23719300
	s_addc_u32 s43, s69, 0
	s_branch .LBB0_289

.LBB0_362:
	s_cmp_lt_i32 s67, 5
	s_cbranch_scc1 .LBB0_416
	s_waitcnt vmcnt(0)
	v_readlane_b32 s4, v232, 0
	v_readlane_b32 s5, v232, 1
	s_waitcnt vmcnt(0)
	s_barrier
	s_and_saveexec_b64 s[6:7], s[4:5]
	s_cbranch_execz .LBB0_415
	s_add_i32 s3, 0, 0x20000
	v_mov_b32_e32 v0, s3
	s_waitcnt vmcnt(0) expcnt(0) lgkmcnt(0)
	buffer_wbl2 sc1
	ds_read_b32 v2, v0
	s_add_i32 s3, 0, 0x20004
	v_mov_b32_e32 v0, s3
	ds_read_b32 v0, v0
	s_waitcnt lgkmcnt(1)
	v_cmp_ne_u32_e32 vcc, 0, v2
	s_cbranch_vccnz .LBB0_379
	s_add_u32 s8, s68, 0x23718200
	s_addc_u32 s9, s69, 0
	s_add_u32 s10, s68, 0x23718400
	s_addc_u32 s11, s69, 0
	s_add_u32 s12, s68, 0x23718500
	s_addc_u32 s13, s69, 0
	s_add_u32 s14, s68, 0x23718600
	s_addc_u32 s15, s69, 0
	s_add_u32 s16, s68, 0x23718700
	s_addc_u32 s17, s69, 0
	s_add_u32 s18, s68, 0x23718800
	s_addc_u32 s19, s69, 0
	s_add_u32 s20, s68, 0x23718900
	s_addc_u32 s21, s69, 0
	s_add_u32 s22, s68, 0x23718a00
	s_addc_u32 s23, s69, 0
	s_add_u32 s24, s68, 0x23718b00
	s_addc_u32 s25, s69, 0
	s_add_u32 s26, s68, 0x23718c00
	s_addc_u32 s27, s69, 0
	s_add_u32 s28, s68, 0x23718d00
	s_addc_u32 s29, s69, 0
	s_add_u32 s30, s68, 0x23718e00
	s_addc_u32 s31, s69, 0
	s_add_u32 s34, s68, 0x23718f00
	s_addc_u32 s35, s69, 0
	s_add_u32 s36, s68, 0x23719000
	s_load_dword s3, s[0:1], 0x110
	s_addc_u32 s37, s69, 0
	s_add_u32 s38, s68, 0x23719100
	s_addc_u32 s39, s69, 0
	s_add_u32 s40, s68, 0x23719200
	s_addc_u32 s41, s69, 0
	s_waitcnt lgkmcnt(0)
	s_mul_i32 s3, s65, s3
	s_add_u32 s42, s68, 0x23719300
	s_mul_i32 s3, s3, s64
	s_addc_u32 s43, s69, 0
	s_mov_b32 s50, 1
	v_mov_b32_e32 v16, 0
	s_branch .LBB0_367

.LBB0_422:
	s_or_b64 exec, exec, s[6:7]
	s_cmp_lt_i32 s67, 6
	s_cbranch_scc1 .LBB0_476
	s_waitcnt vmcnt(0)
	v_readlane_b32 s4, v232, 0
	v_readlane_b32 s5, v232, 1
	s_waitcnt vmcnt(0)
	s_barrier
	s_and_saveexec_b64 s[6:7], s[4:5]
	s_cbranch_execz .LBB0_475
	s_add_i32 s8, 0, 0x20000
	v_mov_b32_e32 v0, s8
	s_waitcnt vmcnt(0) expcnt(0) lgkmcnt(0)
	buffer_wbl2 sc1
	ds_read_b32 v2, v0
	s_add_i32 s8, 0, 0x20004
	v_mov_b32_e32 v0, s8
	ds_read_b32 v0, v0
	s_waitcnt lgkmcnt(1)
	v_cmp_ne_u32_e32 vcc, 0, v2
	s_cbranch_vccnz .LBB0_439
	s_load_dword s4, s[0:1], 0x110
	s_mov_b32 s50, 1
	v_mov_b32_e32 v16, 0
	s_waitcnt lgkmcnt(0)
	s_mul_i32 s8, s65, s4
	s_mul_i32 s3, s8, s3
	s_add_u32 s8, s68, 0x23718200
	s_addc_u32 s9, s69, 0
	s_add_u32 s10, s68, 0x23718400
	s_addc_u32 s11, s69, 0
	s_add_u32 s12, s68, 0x23718500
	s_addc_u32 s13, s69, 0
	s_add_u32 s14, s68, 0x23718600
	s_addc_u32 s15, s69, 0
	s_add_u32 s16, s68, 0x23718700
	s_addc_u32 s17, s69, 0
	s_add_u32 s18, s68, 0x23718800
	s_addc_u32 s19, s69, 0
	s_add_u32 s20, s68, 0x23718900
	s_addc_u32 s21, s69, 0
	s_add_u32 s22, s68, 0x23718a00
	s_addc_u32 s23, s69, 0
	s_add_u32 s24, s68, 0x23718b00
	s_addc_u32 s25, s69, 0
	s_add_u32 s26, s68, 0x23718c00
	s_addc_u32 s27, s69, 0
	s_add_u32 s28, s68, 0x23718d00
	s_addc_u32 s29, s69, 0
	s_add_u32 s30, s68, 0x23718e00
	s_addc_u32 s31, s69, 0
	s_add_u32 s34, s68, 0x23718f00
	s_addc_u32 s35, s69, 0
	s_add_u32 s36, s68, 0x23719000
	s_addc_u32 s37, s69, 0
	s_add_u32 s38, s68, 0x23719100
	s_addc_u32 s39, s69, 0
	s_add_u32 s40, s68, 0x23719200
	s_addc_u32 s41, s69, 0
	s_add_u32 s42, s68, 0x23719300
	s_addc_u32 s43, s69, 0
	s_branch .LBB0_427

.LBB0_501:
	s_cmp_lt_i32 s67, 7
	s_cbranch_scc1 .LBB0_555
	s_waitcnt vmcnt(0)
	v_readlane_b32 s4, v232, 0
	v_readlane_b32 s5, v232, 1
	s_waitcnt vmcnt(0) lgkmcnt(0)
	s_barrier
	s_and_saveexec_b64 s[6:7], s[4:5]
	s_cbranch_execz .LBB0_554
	s_add_i32 s3, 0, 0x20000
	v_mov_b32_e32 v0, s3
	s_waitcnt vmcnt(0) expcnt(0) lgkmcnt(0)
	buffer_wbl2 sc1
	ds_read_b32 v2, v0
	s_add_i32 s3, 0, 0x20004
	v_mov_b32_e32 v0, s3
	ds_read_b32 v0, v0
	s_waitcnt lgkmcnt(1)
	v_cmp_ne_u32_e32 vcc, 0, v2
	s_cbranch_vccnz .LBB0_518
	s_add_u32 s8, s68, 0x23718200
	s_addc_u32 s9, s69, 0
	s_add_u32 s10, s68, 0x23718400
	s_addc_u32 s11, s69, 0
	s_add_u32 s12, s68, 0x23718500
	s_addc_u32 s13, s69, 0
	s_add_u32 s14, s68, 0x23718600
	s_addc_u32 s15, s69, 0
	s_add_u32 s16, s68, 0x23718700
	s_addc_u32 s17, s69, 0
	s_add_u32 s18, s68, 0x23718800
	s_addc_u32 s19, s69, 0
	s_add_u32 s20, s68, 0x23718900
	s_addc_u32 s21, s69, 0
	s_add_u32 s22, s68, 0x23718a00
	s_addc_u32 s23, s69, 0
	s_add_u32 s24, s68, 0x23718b00
	s_addc_u32 s25, s69, 0
	s_add_u32 s26, s68, 0x23718c00
	s_addc_u32 s27, s69, 0
	s_add_u32 s28, s68, 0x23718d00
	s_addc_u32 s29, s69, 0
	s_add_u32 s30, s68, 0x23718e00
	s_addc_u32 s31, s69, 0
	s_add_u32 s34, s68, 0x23718f00
	s_addc_u32 s35, s69, 0
	s_add_u32 s36, s68, 0x23719000
	s_load_dword s3, s[0:1], 0x110
	s_addc_u32 s37, s69, 0
	s_add_u32 s38, s68, 0x23719100
	s_addc_u32 s39, s69, 0
	s_add_u32 s40, s68, 0x23719200
	s_addc_u32 s41, s69, 0
	s_waitcnt lgkmcnt(0)
	s_mul_i32 s3, s65, s3
	s_add_u32 s42, s68, 0x23719300
	s_mul_i32 s3, s3, s64
	s_addc_u32 s43, s69, 0
	s_mov_b32 s50, 1
	v_mov_b32_e32 v16, 0
	s_branch .LBB0_506

.LBB0_563:
	s_or_b64 exec, exec, s[14:15]
	s_cmp_lt_i32 s67, 8
	s_cbranch_scc1 .LBB0_617
	s_waitcnt vmcnt(0)
	v_readlane_b32 s4, v232, 0
	v_readlane_b32 s5, v232, 1
	s_waitcnt vmcnt(0) lgkmcnt(0)
	s_barrier
	s_and_saveexec_b64 s[6:7], s[4:5]
	s_cbranch_execz .LBB0_616
	s_add_i32 s3, 0, 0x20000
	v_mov_b32_e32 v0, s3
	s_waitcnt vmcnt(0) expcnt(0) lgkmcnt(0)
	buffer_wbl2 sc1
	ds_read_b32 v2, v0
	s_add_i32 s3, 0, 0x20004
	v_mov_b32_e32 v0, s3
	ds_read_b32 v0, v0
	s_waitcnt lgkmcnt(1)
	v_cmp_ne_u32_e32 vcc, 0, v2
	s_cbranch_vccnz .LBB0_580
	s_add_u32 s8, s68, 0x23718200
	s_addc_u32 s9, s69, 0
	s_add_u32 s10, s68, 0x23718400
	s_addc_u32 s11, s69, 0
	s_add_u32 s12, s68, 0x23718500
	s_addc_u32 s13, s69, 0
	s_add_u32 s14, s68, 0x23718600
	s_addc_u32 s15, s69, 0
	s_add_u32 s16, s68, 0x23718700
	s_addc_u32 s17, s69, 0
	s_add_u32 s18, s68, 0x23718800
	s_addc_u32 s19, s69, 0
	s_add_u32 s20, s68, 0x23718900
	s_addc_u32 s21, s69, 0
	s_add_u32 s22, s68, 0x23718a00
	s_addc_u32 s23, s69, 0
	s_add_u32 s24, s68, 0x23718b00
	s_addc_u32 s25, s69, 0
	s_add_u32 s26, s68, 0x23718c00
	s_addc_u32 s27, s69, 0
	s_add_u32 s28, s68, 0x23718d00
	s_addc_u32 s29, s69, 0
	s_add_u32 s30, s68, 0x23718e00
	s_addc_u32 s31, s69, 0
	s_add_u32 s34, s68, 0x23718f00
	s_addc_u32 s35, s69, 0
	s_add_u32 s36, s68, 0x23719000
	s_load_dword s3, s[0:1], 0x110
	s_addc_u32 s37, s69, 0
	s_add_u32 s38, s68, 0x23719100
	s_addc_u32 s39, s69, 0
	s_add_u32 s40, s68, 0x23719200
	s_addc_u32 s41, s69, 0
	s_waitcnt lgkmcnt(0)
	s_mul_i32 s3, s65, s3
	s_add_u32 s42, s68, 0x23719300
	s_mul_i32 s3, s3, s64
	s_addc_u32 s43, s69, 0
	s_mov_b32 s50, 1
	v_mov_b32_e32 v16, 0
	s_branch .LBB0_568

.LBB0_694:
	s_cmp_lt_i32 s67, 9
	s_cbranch_scc1 .LBB0_748
	s_waitcnt vmcnt(0)
	v_readlane_b32 s4, v232, 0
	v_readlane_b32 s5, v232, 1
	s_waitcnt vmcnt(0)
	s_barrier
	s_and_saveexec_b64 s[6:7], s[4:5]
	s_cbranch_execz .LBB0_747
	s_add_i32 s3, 0, 0x20000
	v_mov_b32_e32 v0, s3
	s_waitcnt vmcnt(0) expcnt(0) lgkmcnt(0)
	buffer_wbl2 sc1
	ds_read_b32 v2, v0
	s_add_i32 s3, 0, 0x20004
	v_mov_b32_e32 v0, s3
	ds_read_b32 v0, v0
	s_waitcnt lgkmcnt(1)
	v_cmp_ne_u32_e32 vcc, 0, v2
	s_cbranch_vccnz .LBB0_711
	s_add_u32 s8, s68, 0x23718200
	s_addc_u32 s9, s69, 0
	s_add_u32 s10, s68, 0x23718400
	s_addc_u32 s11, s69, 0
	s_add_u32 s12, s68, 0x23718500
	s_addc_u32 s13, s69, 0
	s_add_u32 s14, s68, 0x23718600
	s_addc_u32 s15, s69, 0
	s_add_u32 s16, s68, 0x23718700
	s_addc_u32 s17, s69, 0
	s_add_u32 s18, s68, 0x23718800
	s_addc_u32 s19, s69, 0
	s_add_u32 s20, s68, 0x23718900
	s_addc_u32 s21, s69, 0
	s_add_u32 s22, s68, 0x23718a00
	s_addc_u32 s23, s69, 0
	s_add_u32 s24, s68, 0x23718b00
	s_addc_u32 s25, s69, 0
	s_add_u32 s26, s68, 0x23718c00
	s_addc_u32 s27, s69, 0
	s_add_u32 s28, s68, 0x23718d00
	s_addc_u32 s29, s69, 0
	s_add_u32 s30, s68, 0x23718e00
	s_addc_u32 s31, s69, 0
	s_add_u32 s34, s68, 0x23718f00
	s_addc_u32 s35, s69, 0
	s_add_u32 s36, s68, 0x23719000
	s_load_dword s3, s[0:1], 0x110
	s_addc_u32 s37, s69, 0
	s_add_u32 s38, s68, 0x23719100
	s_addc_u32 s39, s69, 0
	s_add_u32 s40, s68, 0x23719200
	s_addc_u32 s41, s69, 0
	s_waitcnt lgkmcnt(0)
	s_mul_i32 s3, s65, s3
	s_add_u32 s42, s68, 0x23719300
	s_mul_i32 s3, s3, s64
	s_addc_u32 s43, s69, 0
	s_mov_b32 s50, 1
	v_mov_b32_e32 v16, 0
	s_branch .LBB0_699

.LBB0_754:
	s_or_b64 exec, exec, s[36:37]
	s_cmp_lt_i32 s67, 10
	s_cbranch_scc1 .LBB0_808
	s_waitcnt vmcnt(0)
	v_readlane_b32 s4, v232, 0
	v_readlane_b32 s5, v232, 1
	s_waitcnt vmcnt(0) lgkmcnt(0)
	s_barrier
	s_and_saveexec_b64 s[6:7], s[4:5]
	s_cbranch_execz .LBB0_807
	s_add_i32 s3, 0, 0x20000
	v_mov_b32_e32 v0, s3
	s_waitcnt vmcnt(0) expcnt(0) lgkmcnt(0)
	buffer_wbl2 sc1
	ds_read_b32 v2, v0
	s_add_i32 s3, 0, 0x20004
	v_mov_b32_e32 v0, s3
	ds_read_b32 v0, v0
	s_waitcnt lgkmcnt(1)
	v_cmp_ne_u32_e32 vcc, 0, v2
	s_cbranch_vccnz .LBB0_771
	s_add_u32 s8, s68, 0x23718200
	s_addc_u32 s9, s69, 0
	s_add_u32 s10, s68, 0x23718400
	s_addc_u32 s11, s69, 0
	s_add_u32 s12, s68, 0x23718500
	s_addc_u32 s13, s69, 0
	s_add_u32 s14, s68, 0x23718600
	s_addc_u32 s15, s69, 0
	s_add_u32 s16, s68, 0x23718700
	s_addc_u32 s17, s69, 0
	s_add_u32 s18, s68, 0x23718800
	s_addc_u32 s19, s69, 0
	s_add_u32 s20, s68, 0x23718900
	s_addc_u32 s21, s69, 0
	s_add_u32 s22, s68, 0x23718a00
	s_addc_u32 s23, s69, 0
	s_add_u32 s24, s68, 0x23718b00
	s_addc_u32 s25, s69, 0
	s_add_u32 s26, s68, 0x23718c00
	s_addc_u32 s27, s69, 0
	s_add_u32 s28, s68, 0x23718d00
	s_addc_u32 s29, s69, 0
	s_add_u32 s30, s68, 0x23718e00
	s_addc_u32 s31, s69, 0
	s_add_u32 s34, s68, 0x23718f00
	s_addc_u32 s35, s69, 0
	s_add_u32 s36, s68, 0x23719000
	s_load_dword s3, s[0:1], 0x110
	s_addc_u32 s37, s69, 0
	s_add_u32 s38, s68, 0x23719100
	s_addc_u32 s39, s69, 0
	s_add_u32 s40, s68, 0x23719200
	s_addc_u32 s41, s69, 0
	s_waitcnt lgkmcnt(0)
	s_mul_i32 s3, s65, s3
	s_add_u32 s42, s68, 0x23719300
	s_mul_i32 s3, s3, s64
	s_addc_u32 s43, s69, 0
	s_mov_b32 s50, 1
	v_mov_b32_e32 v16, 0
	s_branch .LBB0_759

.LBB0_885:
	s_cmp_lt_i32 s67, 11
	s_cbranch_scc1 .LBB0_939
	s_waitcnt vmcnt(0)
	v_readlane_b32 s4, v232, 0
	v_readlane_b32 s5, v232, 1
	s_waitcnt vmcnt(0)
	s_barrier
	s_and_saveexec_b64 s[6:7], s[4:5]
	s_cbranch_execz .LBB0_938
	s_add_i32 s3, 0, 0x20000
	v_mov_b32_e32 v0, s3
	s_waitcnt vmcnt(0) expcnt(0) lgkmcnt(0)
	buffer_wbl2 sc1
	ds_read_b32 v2, v0
	s_add_i32 s3, 0, 0x20004
	v_mov_b32_e32 v0, s3
	ds_read_b32 v0, v0
	s_waitcnt lgkmcnt(1)
	v_cmp_ne_u32_e32 vcc, 0, v2
	s_cbranch_vccnz .LBB0_902
	s_add_u32 s8, s68, 0x23718200
	s_addc_u32 s9, s69, 0
	s_add_u32 s10, s68, 0x23718400
	s_addc_u32 s11, s69, 0
	s_add_u32 s12, s68, 0x23718500
	s_addc_u32 s13, s69, 0
	s_add_u32 s14, s68, 0x23718600
	s_addc_u32 s15, s69, 0
	s_add_u32 s16, s68, 0x23718700
	s_addc_u32 s17, s69, 0
	s_add_u32 s18, s68, 0x23718800
	s_addc_u32 s19, s69, 0
	s_add_u32 s20, s68, 0x23718900
	s_addc_u32 s21, s69, 0
	s_add_u32 s22, s68, 0x23718a00
	s_addc_u32 s23, s69, 0
	s_add_u32 s24, s68, 0x23718b00
	s_addc_u32 s25, s69, 0
	s_add_u32 s26, s68, 0x23718c00
	s_addc_u32 s27, s69, 0
	s_add_u32 s28, s68, 0x23718d00
	s_addc_u32 s29, s69, 0
	s_add_u32 s30, s68, 0x23718e00
	s_addc_u32 s31, s69, 0
	s_add_u32 s34, s68, 0x23718f00
	s_addc_u32 s35, s69, 0
	s_add_u32 s36, s68, 0x23719000
	s_load_dword s3, s[0:1], 0x110
	s_addc_u32 s37, s69, 0
	s_add_u32 s38, s68, 0x23719100
	s_addc_u32 s39, s69, 0
	s_add_u32 s40, s68, 0x23719200
	s_addc_u32 s41, s69, 0
	s_waitcnt lgkmcnt(0)
	s_mul_i32 s3, s65, s3
	s_add_u32 s42, s68, 0x23719300
	s_mul_i32 s3, s3, s64
	s_addc_u32 s43, s69, 0
	s_mov_b32 s50, 1
	v_mov_b32_e32 v16, 0
	s_branch .LBB0_890

.LBB0_959:
	s_cmp_lt_i32 s67, 12
	s_cbranch_scc1 .LBB0_1013
	s_waitcnt vmcnt(0)
	v_readlane_b32 s4, v232, 0
	v_readlane_b32 s5, v232, 1
	s_waitcnt vmcnt(0)
	s_barrier
	s_and_saveexec_b64 s[6:7], s[4:5]
	s_cbranch_execz .LBB0_1012
	s_add_i32 s3, 0, 0x20000
	v_mov_b32_e32 v0, s3
	s_waitcnt vmcnt(0) expcnt(0) lgkmcnt(0)
	buffer_wbl2 sc1
	ds_read_b32 v2, v0
	s_add_i32 s3, 0, 0x20004
	v_mov_b32_e32 v0, s3
	ds_read_b32 v0, v0
	s_waitcnt lgkmcnt(1)
	v_cmp_ne_u32_e32 vcc, 0, v2
	s_cbranch_vccnz .LBB0_976
	s_add_u32 s8, s68, 0x23718200
	s_addc_u32 s9, s69, 0
	s_add_u32 s10, s68, 0x23718400
	s_addc_u32 s11, s69, 0
	s_add_u32 s12, s68, 0x23718500
	s_addc_u32 s13, s69, 0
	s_add_u32 s14, s68, 0x23718600
	s_addc_u32 s15, s69, 0
	s_add_u32 s16, s68, 0x23718700
	s_addc_u32 s17, s69, 0
	s_add_u32 s18, s68, 0x23718800
	s_addc_u32 s19, s69, 0
	s_add_u32 s20, s68, 0x23718900
	s_addc_u32 s21, s69, 0
	s_add_u32 s22, s68, 0x23718a00
	s_addc_u32 s23, s69, 0
	s_add_u32 s24, s68, 0x23718b00
	s_addc_u32 s25, s69, 0
	s_add_u32 s26, s68, 0x23718c00
	s_addc_u32 s27, s69, 0
	s_add_u32 s28, s68, 0x23718d00
	s_addc_u32 s29, s69, 0
	s_add_u32 s30, s68, 0x23718e00
	s_addc_u32 s31, s69, 0
	s_add_u32 s34, s68, 0x23718f00
	s_addc_u32 s35, s69, 0
	s_add_u32 s36, s68, 0x23719000
	s_load_dword s3, s[0:1], 0x110
	s_addc_u32 s37, s69, 0
	s_add_u32 s38, s68, 0x23719100
	s_addc_u32 s39, s69, 0
	s_add_u32 s40, s68, 0x23719200
	s_addc_u32 s41, s69, 0
	s_waitcnt lgkmcnt(0)
	s_mul_i32 s3, s65, s3
	s_add_u32 s42, s68, 0x23719300
	s_mul_i32 s3, s3, s64
	s_addc_u32 s43, s69, 0
	s_mov_b32 s50, 1
	v_mov_b32_e32 v16, 0
	s_branch .LBB0_964

.LBB0_1019:
	s_or_b64 exec, exec, s[6:7]
	s_cmp_lt_i32 s67, 13
	s_cbranch_scc1 .LBB0_1073
	s_waitcnt vmcnt(0)
	v_readlane_b32 s4, v232, 0
	v_readlane_b32 s5, v232, 1
	s_waitcnt vmcnt(0)
	s_barrier
	s_and_saveexec_b64 s[6:7], s[4:5]
	s_cbranch_execz .LBB0_1072
	s_add_i32 s4, 0, 0x20000
	v_mov_b32_e32 v0, s4
	s_waitcnt vmcnt(0) expcnt(0) lgkmcnt(0)
	buffer_wbl2 sc1
	ds_read_b32 v2, v0
	s_add_i32 s4, 0, 0x20004
	v_mov_b32_e32 v0, s4
	ds_read_b32 v0, v0
	s_waitcnt lgkmcnt(1)
	v_cmp_ne_u32_e32 vcc, 0, v2
	s_cbranch_vccnz .LBB0_1036
	s_add_u32 s8, s68, 0x23718200
	s_addc_u32 s9, s69, 0
	s_add_u32 s10, s68, 0x23718400
	s_addc_u32 s11, s69, 0
	s_add_u32 s12, s68, 0x23718500
	s_addc_u32 s13, s69, 0
	s_add_u32 s14, s68, 0x23718600
	s_addc_u32 s15, s69, 0
	s_add_u32 s16, s68, 0x23718700
	s_addc_u32 s17, s69, 0
	s_add_u32 s18, s68, 0x23718800
	s_addc_u32 s19, s69, 0
	s_add_u32 s20, s68, 0x23718900
	s_addc_u32 s21, s69, 0
	s_add_u32 s22, s68, 0x23718a00
	s_addc_u32 s23, s69, 0
	s_add_u32 s24, s68, 0x23718b00
	s_addc_u32 s25, s69, 0
	s_add_u32 s26, s68, 0x23718c00
	s_addc_u32 s27, s69, 0
	s_add_u32 s28, s68, 0x23718d00
	s_addc_u32 s29, s69, 0
	s_add_u32 s30, s68, 0x23718e00
	s_addc_u32 s31, s69, 0
	s_add_u32 s34, s68, 0x23718f00
	s_addc_u32 s35, s69, 0
	s_add_u32 s36, s68, 0x23719000
	s_load_dword s4, s[0:1], 0x110
	s_addc_u32 s37, s69, 0
	s_add_u32 s38, s68, 0x23719100
	s_addc_u32 s39, s69, 0
	s_add_u32 s40, s68, 0x23719200
	s_addc_u32 s41, s69, 0
	s_waitcnt lgkmcnt(0)
	s_mul_i32 s4, s65, s4
	s_add_u32 s42, s68, 0x23719300
	s_mul_i32 s3, s4, s3
	s_addc_u32 s43, s69, 0
	s_mov_b32 s50, 1
	v_mov_b32_e32 v16, 0
	s_branch .LBB0_1024

.LBB0_1094:
	s_cmp_lt_i32 s67, 14
	s_cbranch_scc1 .LBB0_1148
	s_waitcnt vmcnt(0)
	v_readlane_b32 s4, v232, 0
	v_readlane_b32 s5, v232, 1
	s_waitcnt vmcnt(0)
	s_barrier
	s_and_saveexec_b64 s[6:7], s[4:5]
	s_cbranch_execz .LBB0_1147
	s_add_i32 s4, 0, 0x20000
	v_mov_b32_e32 v0, s4
	s_waitcnt vmcnt(0) expcnt(0) lgkmcnt(0)
	buffer_wbl2 sc1
	ds_read_b32 v2, v0
	s_add_i32 s4, 0, 0x20004
	v_mov_b32_e32 v0, s4
	ds_read_b32 v0, v0
	s_waitcnt lgkmcnt(1)
	v_cmp_ne_u32_e32 vcc, 0, v2
	s_cbranch_vccnz .LBB0_1111
	s_add_u32 s8, s68, 0x23718200
	s_addc_u32 s9, s69, 0
	s_add_u32 s10, s68, 0x23718400
	s_addc_u32 s11, s69, 0
	s_add_u32 s12, s68, 0x23718500
	s_addc_u32 s13, s69, 0
	s_add_u32 s14, s68, 0x23718600
	s_addc_u32 s15, s69, 0
	s_add_u32 s16, s68, 0x23718700
	s_addc_u32 s17, s69, 0
	s_add_u32 s18, s68, 0x23718800
	s_addc_u32 s19, s69, 0
	s_add_u32 s20, s68, 0x23718900
	s_addc_u32 s21, s69, 0
	s_add_u32 s22, s68, 0x23718a00
	s_addc_u32 s23, s69, 0
	s_add_u32 s24, s68, 0x23718b00
	s_addc_u32 s25, s69, 0
	s_add_u32 s26, s68, 0x23718c00
	s_addc_u32 s27, s69, 0
	s_add_u32 s28, s68, 0x23718d00
	s_addc_u32 s29, s69, 0
	s_add_u32 s30, s68, 0x23718e00
	s_addc_u32 s31, s69, 0
	s_add_u32 s34, s68, 0x23718f00
	s_addc_u32 s35, s69, 0
	s_add_u32 s36, s68, 0x23719000
	s_load_dword s4, s[0:1], 0x110
	s_addc_u32 s37, s69, 0
	s_add_u32 s38, s68, 0x23719100
	s_addc_u32 s39, s69, 0
	s_add_u32 s40, s68, 0x23719200
	s_addc_u32 s41, s69, 0
	s_waitcnt lgkmcnt(0)
	s_mul_i32 s4, s65, s4
	s_add_u32 s42, s68, 0x23719300
	s_mul_i32 s3, s4, s3
	s_addc_u32 s43, s69, 0
	s_mov_b32 s50, 1
	v_mov_b32_e32 v16, 0
	s_branch .LBB0_1099

.LBB0_1172:
	s_cmp_lt_i32 s67, 15
	s_cbranch_scc1 .LBB0_1226
	s_waitcnt vmcnt(0)
	v_readlane_b32 s4, v232, 0
	v_readlane_b32 s5, v232, 1
	s_waitcnt vmcnt(0)
	s_barrier
	s_and_saveexec_b64 s[6:7], s[4:5]
	s_cbranch_execz .LBB0_1225
	s_add_i32 s3, 0, 0x20000
	v_mov_b32_e32 v0, s3
	s_waitcnt vmcnt(0) expcnt(0) lgkmcnt(0)
	buffer_wbl2 sc1
	ds_read_b32 v2, v0
	s_add_i32 s3, 0, 0x20004
	v_mov_b32_e32 v0, s3
	ds_read_b32 v0, v0
	s_waitcnt lgkmcnt(1)
	v_cmp_ne_u32_e32 vcc, 0, v2
	s_cbranch_vccnz .LBB0_1189
	s_add_u32 s8, s68, 0x23718200
	s_addc_u32 s9, s69, 0
	s_add_u32 s10, s68, 0x23718400
	s_addc_u32 s11, s69, 0
	s_add_u32 s12, s68, 0x23718500
	s_addc_u32 s13, s69, 0
	s_add_u32 s14, s68, 0x23718600
	s_addc_u32 s15, s69, 0
	s_add_u32 s16, s68, 0x23718700
	s_addc_u32 s17, s69, 0
	s_add_u32 s18, s68, 0x23718800
	s_addc_u32 s19, s69, 0
	s_add_u32 s20, s68, 0x23718900
	s_addc_u32 s21, s69, 0
	s_add_u32 s22, s68, 0x23718a00
	s_addc_u32 s23, s69, 0
	s_add_u32 s24, s68, 0x23718b00
	s_addc_u32 s25, s69, 0
	s_add_u32 s26, s68, 0x23718c00
	s_addc_u32 s27, s69, 0
	s_add_u32 s28, s68, 0x23718d00
	s_addc_u32 s29, s69, 0
	s_add_u32 s30, s68, 0x23718e00
	s_addc_u32 s31, s69, 0
	s_add_u32 s34, s68, 0x23718f00
	s_addc_u32 s35, s69, 0
	s_add_u32 s36, s68, 0x23719000
	s_load_dword s3, s[0:1], 0x110
	s_addc_u32 s37, s69, 0
	s_add_u32 s38, s68, 0x23719100
	s_addc_u32 s39, s69, 0
	s_add_u32 s40, s68, 0x23719200
	s_addc_u32 s41, s69, 0
	s_waitcnt lgkmcnt(0)
	s_mul_i32 s3, s65, s3
	s_add_u32 s42, s68, 0x23719300
	s_mul_i32 s3, s3, s64
	s_addc_u32 s43, s69, 0
	s_mov_b32 s50, 1
	v_mov_b32_e32 v16, 0
	s_branch .LBB0_1177

.LBB0_1232:
	s_or_b64 exec, exec, s[6:7]
	s_cmp_lt_i32 s67, 16
	s_cbranch_scc1 .LBB0_1286
	s_waitcnt vmcnt(0)
	v_readlane_b32 s4, v232, 0
	v_readlane_b32 s5, v232, 1
	s_waitcnt vmcnt(0)
	s_barrier
	s_and_saveexec_b64 s[6:7], s[4:5]
	s_cbranch_execz .LBB0_1285
	s_add_i32 s4, 0, 0x20000
	v_mov_b32_e32 v0, s4
	s_waitcnt vmcnt(0) expcnt(0) lgkmcnt(0)
	buffer_wbl2 sc1
	ds_read_b32 v2, v0
	s_add_i32 s4, 0, 0x20004
	v_mov_b32_e32 v0, s4
	ds_read_b32 v0, v0
	s_waitcnt lgkmcnt(1)
	v_cmp_ne_u32_e32 vcc, 0, v2
	s_cbranch_vccnz .LBB0_1249
	s_add_u32 s8, s68, 0x23718200
	s_addc_u32 s9, s69, 0
	s_add_u32 s10, s68, 0x23718400
	s_addc_u32 s11, s69, 0
	s_add_u32 s12, s68, 0x23718500
	s_addc_u32 s13, s69, 0
	s_add_u32 s14, s68, 0x23718600
	s_addc_u32 s15, s69, 0
	s_add_u32 s16, s68, 0x23718700
	s_addc_u32 s17, s69, 0
	s_add_u32 s18, s68, 0x23718800
	s_addc_u32 s19, s69, 0
	s_add_u32 s20, s68, 0x23718900
	s_addc_u32 s21, s69, 0
	s_add_u32 s22, s68, 0x23718a00
	s_addc_u32 s23, s69, 0
	s_add_u32 s24, s68, 0x23718b00
	s_addc_u32 s25, s69, 0
	s_add_u32 s26, s68, 0x23718c00
	s_addc_u32 s27, s69, 0
	s_add_u32 s28, s68, 0x23718d00
	s_addc_u32 s29, s69, 0
	s_add_u32 s30, s68, 0x23718e00
	s_addc_u32 s31, s69, 0
	s_add_u32 s34, s68, 0x23718f00
	s_addc_u32 s35, s69, 0
	s_add_u32 s36, s68, 0x23719000
	s_load_dword s4, s[0:1], 0x110
	s_addc_u32 s37, s69, 0
	s_add_u32 s38, s68, 0x23719100
	s_addc_u32 s39, s69, 0
	s_add_u32 s40, s68, 0x23719200
	s_addc_u32 s41, s69, 0
	s_waitcnt lgkmcnt(0)
	s_mul_i32 s4, s65, s4
	s_add_u32 s42, s68, 0x23719300
	s_mul_i32 s3, s4, s3
	s_addc_u32 s43, s69, 0
	s_mov_b32 s50, 1
	v_mov_b32_e32 v16, 0
	s_branch .LBB0_1237

.LBB0_1307:
	s_cmp_lt_i32 s67, 17
	s_cbranch_scc1 .LBB0_1361
	s_waitcnt vmcnt(0)
	v_readlane_b32 s4, v232, 0
	v_readlane_b32 s5, v232, 1
	s_waitcnt vmcnt(0)
	s_barrier
	s_and_saveexec_b64 s[6:7], s[4:5]
	s_cbranch_execz .LBB0_1360
	s_add_i32 s4, 0, 0x20000
	v_mov_b32_e32 v0, s4
	s_waitcnt vmcnt(0) expcnt(0) lgkmcnt(0)
	buffer_wbl2 sc1
	ds_read_b32 v2, v0
	s_add_i32 s4, 0, 0x20004
	v_mov_b32_e32 v0, s4
	ds_read_b32 v0, v0
	s_waitcnt lgkmcnt(1)
	v_cmp_ne_u32_e32 vcc, 0, v2
	s_cbranch_vccnz .LBB0_1324
	s_add_u32 s8, s68, 0x23718200
	s_addc_u32 s9, s69, 0
	s_add_u32 s10, s68, 0x23718400
	s_addc_u32 s11, s69, 0
	s_add_u32 s12, s68, 0x23718500
	s_addc_u32 s13, s69, 0
	s_add_u32 s14, s68, 0x23718600
	s_addc_u32 s15, s69, 0
	s_add_u32 s16, s68, 0x23718700
	s_addc_u32 s17, s69, 0
	s_add_u32 s18, s68, 0x23718800
	s_addc_u32 s19, s69, 0
	s_add_u32 s20, s68, 0x23718900
	s_addc_u32 s21, s69, 0
	s_add_u32 s22, s68, 0x23718a00
	s_addc_u32 s23, s69, 0
	s_add_u32 s24, s68, 0x23718b00
	s_addc_u32 s25, s69, 0
	s_add_u32 s26, s68, 0x23718c00
	s_addc_u32 s27, s69, 0
	s_add_u32 s28, s68, 0x23718d00
	s_addc_u32 s29, s69, 0
	s_add_u32 s30, s68, 0x23718e00
	s_addc_u32 s31, s69, 0
	s_add_u32 s34, s68, 0x23718f00
	s_addc_u32 s35, s69, 0
	s_add_u32 s36, s68, 0x23719000
	s_load_dword s4, s[0:1], 0x110
	s_addc_u32 s37, s69, 0
	s_add_u32 s38, s68, 0x23719100
	s_addc_u32 s39, s69, 0
	s_add_u32 s40, s68, 0x23719200
	s_addc_u32 s41, s69, 0
	s_waitcnt lgkmcnt(0)
	s_mul_i32 s4, s65, s4
	s_add_u32 s42, s68, 0x23719300
	s_mul_i32 s3, s4, s3
	s_addc_u32 s43, s69, 0
	s_mov_b32 s50, 1
	v_mov_b32_e32 v16, 0
	s_branch .LBB0_1312

.LBB0_1385:
	s_cmp_lt_i32 s67, 18
	s_cbranch_scc1 .LBB0_1439
	s_waitcnt vmcnt(0)
	v_readlane_b32 s4, v232, 0
	v_readlane_b32 s5, v232, 1
	s_waitcnt vmcnt(0)
	s_barrier
	s_and_saveexec_b64 s[6:7], s[4:5]
	s_cbranch_execz .LBB0_1438
	s_add_i32 s3, 0, 0x20000
	v_mov_b32_e32 v0, s3
	s_waitcnt vmcnt(0) expcnt(0) lgkmcnt(0)
	buffer_wbl2 sc1
	ds_read_b32 v2, v0
	s_add_i32 s3, 0, 0x20004
	v_mov_b32_e32 v0, s3
	ds_read_b32 v0, v0
	s_waitcnt lgkmcnt(1)
	v_cmp_ne_u32_e32 vcc, 0, v2
	s_cbranch_vccnz .LBB0_1402
	s_add_u32 s8, s68, 0x23718200
	s_addc_u32 s9, s69, 0
	s_add_u32 s10, s68, 0x23718400
	s_addc_u32 s11, s69, 0
	s_add_u32 s12, s68, 0x23718500
	s_addc_u32 s13, s69, 0
	s_add_u32 s14, s68, 0x23718600
	s_addc_u32 s15, s69, 0
	s_add_u32 s16, s68, 0x23718700
	s_addc_u32 s17, s69, 0
	s_add_u32 s18, s68, 0x23718800
	s_addc_u32 s19, s69, 0
	s_add_u32 s20, s68, 0x23718900
	s_addc_u32 s21, s69, 0
	s_add_u32 s22, s68, 0x23718a00
	s_addc_u32 s23, s69, 0
	s_add_u32 s24, s68, 0x23718b00
	s_addc_u32 s25, s69, 0
	s_add_u32 s26, s68, 0x23718c00
	s_addc_u32 s27, s69, 0
	s_add_u32 s28, s68, 0x23718d00
	s_addc_u32 s29, s69, 0
	s_add_u32 s30, s68, 0x23718e00
	s_addc_u32 s31, s69, 0
	s_add_u32 s34, s68, 0x23718f00
	s_addc_u32 s35, s69, 0
	s_add_u32 s36, s68, 0x23719000
	s_load_dword s3, s[0:1], 0x110
	s_addc_u32 s37, s69, 0
	s_add_u32 s38, s68, 0x23719100
	s_addc_u32 s39, s69, 0
	s_add_u32 s40, s68, 0x23719200
	s_addc_u32 s41, s69, 0
	s_waitcnt lgkmcnt(0)
	s_mul_i32 s3, s65, s3
	s_add_u32 s42, s68, 0x23719300
	s_mul_i32 s3, s3, s64
	s_addc_u32 s43, s69, 0
	s_mov_b32 s50, 1
	v_mov_b32_e32 v16, 0
	s_branch .LBB0_1390

.LBB0_1445:
	s_or_b64 exec, exec, s[6:7]
	s_cmp_lt_i32 s67, 19
	s_cbranch_scc1 .LBB0_1499
	s_waitcnt vmcnt(0)
	v_readlane_b32 s4, v232, 0
	v_readlane_b32 s5, v232, 1
	s_waitcnt vmcnt(0)
	s_barrier
	s_and_saveexec_b64 s[6:7], s[4:5]
	s_cbranch_execz .LBB0_1498
	s_add_i32 s4, 0, 0x20000
	v_mov_b32_e32 v0, s4
	s_waitcnt vmcnt(0) expcnt(0) lgkmcnt(0)
	buffer_wbl2 sc1
	ds_read_b32 v2, v0
	s_add_i32 s4, 0, 0x20004
	v_mov_b32_e32 v0, s4
	ds_read_b32 v0, v0
	s_waitcnt lgkmcnt(1)
	v_cmp_ne_u32_e32 vcc, 0, v2
	s_cbranch_vccnz .LBB0_1462
	s_add_u32 s8, s68, 0x23718200
	s_addc_u32 s9, s69, 0
	s_add_u32 s10, s68, 0x23718400
	s_addc_u32 s11, s69, 0
	s_add_u32 s12, s68, 0x23718500
	s_addc_u32 s13, s69, 0
	s_add_u32 s14, s68, 0x23718600
	s_addc_u32 s15, s69, 0
	s_add_u32 s16, s68, 0x23718700
	s_addc_u32 s17, s69, 0
	s_add_u32 s18, s68, 0x23718800
	s_addc_u32 s19, s69, 0
	s_add_u32 s20, s68, 0x23718900
	s_addc_u32 s21, s69, 0
	s_add_u32 s22, s68, 0x23718a00
	s_addc_u32 s23, s69, 0
	s_add_u32 s24, s68, 0x23718b00
	s_addc_u32 s25, s69, 0
	s_add_u32 s26, s68, 0x23718c00
	s_addc_u32 s27, s69, 0
	s_add_u32 s28, s68, 0x23718d00
	s_addc_u32 s29, s69, 0
	s_add_u32 s30, s68, 0x23718e00
	s_addc_u32 s31, s69, 0
	s_add_u32 s34, s68, 0x23718f00
	s_addc_u32 s35, s69, 0
	s_add_u32 s36, s68, 0x23719000
	s_load_dword s4, s[0:1], 0x110
	s_addc_u32 s37, s69, 0
	s_add_u32 s38, s68, 0x23719100
	s_addc_u32 s39, s69, 0
	s_add_u32 s40, s68, 0x23719200
	s_addc_u32 s41, s69, 0
	s_waitcnt lgkmcnt(0)
	s_mul_i32 s4, s65, s4
	s_add_u32 s42, s68, 0x23719300
	s_mul_i32 s3, s4, s3
	s_addc_u32 s43, s69, 0
	s_mov_b32 s50, 1
	v_mov_b32_e32 v16, 0
	s_branch .LBB0_1450

.LBB0_1512:
	s_or_b64 exec, exec, s[78:79]
	s_cmp_lt_u32 s67, 20
	s_cbranch_scc1 .LBB0_1566
	s_waitcnt vmcnt(0)
	v_readlane_b32 s4, v232, 0
	v_readlane_b32 s5, v232, 1
	s_waitcnt vmcnt(0)
	s_barrier
	s_and_saveexec_b64 s[6:7], s[4:5]
	s_cbranch_execz .LBB0_1565
	s_add_i32 s3, 0, 0x20000
	v_mov_b32_e32 v0, s3
	s_waitcnt vmcnt(0) expcnt(0) lgkmcnt(0)
	buffer_wbl2 sc1
	ds_read_b32 v2, v0
	s_add_i32 s3, 0, 0x20004
	v_mov_b32_e32 v0, s3
	ds_read_b32 v0, v0
	s_waitcnt lgkmcnt(1)
	v_cmp_ne_u32_e32 vcc, 0, v2
	s_cbranch_vccnz .LBB0_1529
	s_add_u32 s8, s68, 0x23718200
	s_addc_u32 s9, s69, 0
	s_add_u32 s10, s68, 0x23718400
	s_addc_u32 s11, s69, 0
	s_add_u32 s12, s68, 0x23718500
	s_addc_u32 s13, s69, 0
	s_add_u32 s14, s68, 0x23718600
	s_addc_u32 s15, s69, 0
	s_add_u32 s16, s68, 0x23718700
	s_addc_u32 s17, s69, 0
	s_add_u32 s18, s68, 0x23718800
	s_addc_u32 s19, s69, 0
	s_add_u32 s20, s68, 0x23718900
	s_addc_u32 s21, s69, 0
	s_add_u32 s22, s68, 0x23718a00
	s_addc_u32 s23, s69, 0
	s_add_u32 s24, s68, 0x23718b00
	s_addc_u32 s25, s69, 0
	s_add_u32 s26, s68, 0x23718c00
	s_addc_u32 s27, s69, 0
	s_add_u32 s28, s68, 0x23718d00
	s_addc_u32 s29, s69, 0
	s_add_u32 s30, s68, 0x23718e00
	s_addc_u32 s31, s69, 0
	s_add_u32 s34, s68, 0x23718f00
	s_addc_u32 s35, s69, 0
	s_add_u32 s36, s68, 0x23719000
	s_load_dword s3, s[0:1], 0x110
	s_addc_u32 s37, s69, 0
	s_add_u32 s38, s68, 0x23719100
	s_addc_u32 s39, s69, 0
	s_add_u32 s40, s68, 0x23719200
	s_addc_u32 s41, s69, 0
	s_waitcnt lgkmcnt(0)
	s_mul_i32 s3, s65, s3
	s_add_u32 s42, s68, 0x23719300
	s_mul_i32 s3, s3, s64
	s_addc_u32 s43, s69, 0
	s_mov_b32 s50, 1
	v_mov_b32_e32 v16, 0
	s_branch .LBB0_1517

.LBB0_1634:
	s_cmp_gt_i32 s67, 20
	s_cbranch_scc0 .LBB0_1688
	s_waitcnt vmcnt(0)
	v_readlane_b32 s4, v232, 0
	v_readlane_b32 s5, v232, 1
	s_waitcnt vmcnt(0)
	s_barrier
	s_and_saveexec_b64 s[6:7], s[4:5]
	s_cbranch_execz .LBB0_1687
	s_add_i32 s4, 0, 0x20000
	v_mov_b32_e32 v0, s4
	s_waitcnt vmcnt(0) expcnt(0) lgkmcnt(0)
	buffer_wbl2 sc1
	ds_read_b32 v2, v0
	s_add_i32 s4, 0, 0x20004
	v_mov_b32_e32 v0, s4
	ds_read_b32 v0, v0
	s_waitcnt lgkmcnt(1)
	v_cmp_ne_u32_e32 vcc, 0, v2
	s_cbranch_vccnz .LBB0_1651
	s_add_u32 s8, s68, 0x23718200
	s_addc_u32 s9, s69, 0
	s_add_u32 s10, s68, 0x23718400
	s_addc_u32 s11, s69, 0
	s_add_u32 s12, s68, 0x23718500
	s_addc_u32 s13, s69, 0
	s_add_u32 s14, s68, 0x23718600
	s_addc_u32 s15, s69, 0
	s_add_u32 s16, s68, 0x23718700
	s_addc_u32 s17, s69, 0
	s_add_u32 s18, s68, 0x23718800
	s_addc_u32 s19, s69, 0
	s_add_u32 s20, s68, 0x23718900
	s_addc_u32 s21, s69, 0
	s_add_u32 s22, s68, 0x23718a00
	s_addc_u32 s23, s69, 0
	s_add_u32 s24, s68, 0x23718b00
	s_addc_u32 s25, s69, 0
	s_add_u32 s26, s68, 0x23718c00
	s_addc_u32 s27, s69, 0
	s_add_u32 s28, s68, 0x23718d00
	s_addc_u32 s29, s69, 0
	s_add_u32 s30, s68, 0x23718e00
	s_addc_u32 s31, s69, 0
	s_add_u32 s34, s68, 0x23718f00
	s_addc_u32 s35, s69, 0
	s_add_u32 s36, s68, 0x23719000
	s_load_dword s4, s[0:1], 0x110
	s_addc_u32 s37, s69, 0
	s_add_u32 s38, s68, 0x23719100
	s_addc_u32 s39, s69, 0
	s_add_u32 s40, s68, 0x23719200
	s_addc_u32 s41, s69, 0
	s_waitcnt lgkmcnt(0)
	s_mul_i32 s4, s65, s4
	s_add_u32 s42, s68, 0x23719300
	s_mul_i32 s3, s4, s3
	s_addc_u32 s43, s69, 0
	s_mov_b32 s50, 1
	v_mov_b32_e32 v16, 0
	s_branch .LBB0_1639

.LBB0_1694:
	s_or_b64 exec, exec, s[6:7]
	s_cmp_lt_i32 s67, 22
	s_cbranch_scc1 .LBB0_1748
	s_waitcnt vmcnt(0)
	v_readlane_b32 s4, v232, 0
	v_readlane_b32 s5, v232, 1
	s_waitcnt vmcnt(0)
	s_barrier
	s_and_saveexec_b64 s[6:7], s[4:5]
	s_cbranch_execz .LBB0_1747
	s_add_i32 s4, 0, 0x20000
	v_mov_b32_e32 v0, s4
	s_waitcnt vmcnt(0) expcnt(0) lgkmcnt(0)
	buffer_wbl2 sc1
	ds_read_b32 v2, v0
	s_add_i32 s4, 0, 0x20004
	v_mov_b32_e32 v0, s4
	ds_read_b32 v0, v0
	s_waitcnt lgkmcnt(1)
	v_cmp_ne_u32_e32 vcc, 0, v2
	s_cbranch_vccnz .LBB0_1711
	s_add_u32 s8, s68, 0x23718200
	s_addc_u32 s9, s69, 0
	s_add_u32 s10, s68, 0x23718400
	s_addc_u32 s11, s69, 0
	s_add_u32 s12, s68, 0x23718500
	s_addc_u32 s13, s69, 0
	s_add_u32 s14, s68, 0x23718600
	s_addc_u32 s15, s69, 0
	s_add_u32 s16, s68, 0x23718700
	s_addc_u32 s17, s69, 0
	s_add_u32 s18, s68, 0x23718800
	s_addc_u32 s19, s69, 0
	s_add_u32 s20, s68, 0x23718900
	s_addc_u32 s21, s69, 0
	s_add_u32 s22, s68, 0x23718a00
	s_addc_u32 s23, s69, 0
	s_add_u32 s24, s68, 0x23718b00
	s_addc_u32 s25, s69, 0
	s_add_u32 s26, s68, 0x23718c00
	s_addc_u32 s27, s69, 0
	s_add_u32 s28, s68, 0x23718d00
	s_addc_u32 s29, s69, 0
	s_add_u32 s30, s68, 0x23718e00
	s_addc_u32 s31, s69, 0
	s_add_u32 s34, s68, 0x23718f00
	s_addc_u32 s35, s69, 0
	s_add_u32 s36, s68, 0x23719000
	s_load_dword s4, s[0:1], 0x110
	s_addc_u32 s37, s69, 0
	s_add_u32 s38, s68, 0x23719100
	s_addc_u32 s39, s69, 0
	s_add_u32 s40, s68, 0x23719200
	s_addc_u32 s41, s69, 0
	s_waitcnt lgkmcnt(0)
	s_mul_i32 s4, s65, s4
	s_add_u32 s42, s68, 0x23719300
	s_mul_i32 s3, s4, s3
	s_addc_u32 s43, s69, 0
	s_mov_b32 s50, 1
	v_mov_b32_e32 v16, 0
	s_branch .LBB0_1699

.LBB0_1769:
	s_cmp_lt_i32 s67, 23
	s_cbranch_scc1 .LBB0_1823
	s_waitcnt vmcnt(0)
	v_readlane_b32 s4, v232, 0
	v_readlane_b32 s5, v232, 1
	s_waitcnt vmcnt(0)
	s_barrier
	s_and_saveexec_b64 s[6:7], s[4:5]
	s_cbranch_execz .LBB0_1822
	s_add_i32 s4, 0, 0x20000
	v_mov_b32_e32 v0, s4
	s_waitcnt vmcnt(0) expcnt(0) lgkmcnt(0)
	buffer_wbl2 sc1
	ds_read_b32 v2, v0
	s_add_i32 s4, 0, 0x20004
	v_mov_b32_e32 v0, s4
	ds_read_b32 v0, v0
	s_waitcnt lgkmcnt(1)
	v_cmp_ne_u32_e32 vcc, 0, v2
	s_cbranch_vccnz .LBB0_1786
	s_add_u32 s8, s68, 0x23718200
	s_addc_u32 s9, s69, 0
	s_add_u32 s10, s68, 0x23718400
	s_addc_u32 s11, s69, 0
	s_add_u32 s12, s68, 0x23718500
	s_addc_u32 s13, s69, 0
	s_add_u32 s14, s68, 0x23718600
	s_addc_u32 s15, s69, 0
	s_add_u32 s16, s68, 0x23718700
	s_addc_u32 s17, s69, 0
	s_add_u32 s18, s68, 0x23718800
	s_addc_u32 s19, s69, 0
	s_add_u32 s20, s68, 0x23718900
	s_addc_u32 s21, s69, 0
	s_add_u32 s22, s68, 0x23718a00
	s_addc_u32 s23, s69, 0
	s_add_u32 s24, s68, 0x23718b00
	s_addc_u32 s25, s69, 0
	s_add_u32 s26, s68, 0x23718c00
	s_addc_u32 s27, s69, 0
	s_add_u32 s28, s68, 0x23718d00
	s_addc_u32 s29, s69, 0
	s_add_u32 s30, s68, 0x23718e00
	s_addc_u32 s31, s69, 0
	s_add_u32 s34, s68, 0x23718f00
	s_addc_u32 s35, s69, 0
	s_add_u32 s36, s68, 0x23719000
	s_load_dword s4, s[0:1], 0x110
	s_addc_u32 s37, s69, 0
	s_add_u32 s38, s68, 0x23719100
	s_addc_u32 s39, s69, 0
	s_add_u32 s40, s68, 0x23719200
	s_addc_u32 s41, s69, 0
	s_waitcnt lgkmcnt(0)
	s_mul_i32 s4, s65, s4
	s_add_u32 s42, s68, 0x23719300
	s_mul_i32 s3, s4, s3
	s_addc_u32 s43, s69, 0
	s_mov_b32 s50, 1
	v_mov_b32_e32 v16, 0
	s_branch .LBB0_1774

.LBB0_1847:
	s_cmp_lt_i32 s67, 24
	s_cbranch_scc1 .LBB0_1901
	s_waitcnt vmcnt(0)
	v_readlane_b32 s4, v232, 0
	v_readlane_b32 s5, v232, 1
	s_waitcnt vmcnt(0)
	s_barrier
	s_and_saveexec_b64 s[6:7], s[4:5]
	s_cbranch_execz .LBB0_1900
	s_add_i32 s3, 0, 0x20000
	v_mov_b32_e32 v0, s3
	s_waitcnt vmcnt(0) expcnt(0) lgkmcnt(0)
	buffer_wbl2 sc1
	ds_read_b32 v2, v0
	s_add_i32 s3, 0, 0x20004
	v_mov_b32_e32 v0, s3
	ds_read_b32 v0, v0
	s_waitcnt lgkmcnt(1)
	v_cmp_ne_u32_e32 vcc, 0, v2
	s_cbranch_vccnz .LBB0_1864
	s_add_u32 s8, s68, 0x23718200
	s_addc_u32 s9, s69, 0
	s_add_u32 s10, s68, 0x23718400
	s_addc_u32 s11, s69, 0
	s_add_u32 s12, s68, 0x23718500
	s_addc_u32 s13, s69, 0
	s_add_u32 s14, s68, 0x23718600
	s_addc_u32 s15, s69, 0
	s_add_u32 s16, s68, 0x23718700
	s_addc_u32 s17, s69, 0
	s_add_u32 s18, s68, 0x23718800
	s_addc_u32 s19, s69, 0
	s_add_u32 s20, s68, 0x23718900
	s_addc_u32 s21, s69, 0
	s_add_u32 s22, s68, 0x23718a00
	s_addc_u32 s23, s69, 0
	s_add_u32 s24, s68, 0x23718b00
	s_addc_u32 s25, s69, 0
	s_add_u32 s26, s68, 0x23718c00
	s_addc_u32 s27, s69, 0
	s_add_u32 s28, s68, 0x23718d00
	s_addc_u32 s29, s69, 0
	s_add_u32 s30, s68, 0x23718e00
	s_addc_u32 s31, s69, 0
	s_add_u32 s34, s68, 0x23718f00
	s_addc_u32 s35, s69, 0
	s_add_u32 s36, s68, 0x23719000
	s_load_dword s3, s[0:1], 0x110
	s_addc_u32 s37, s69, 0
	s_add_u32 s38, s68, 0x23719100
	s_addc_u32 s39, s69, 0
	s_add_u32 s40, s68, 0x23719200
	s_addc_u32 s41, s69, 0
	s_waitcnt lgkmcnt(0)
	s_mul_i32 s3, s65, s3
	s_add_u32 s42, s68, 0x23719300
	s_mul_i32 s3, s3, s64
	s_addc_u32 s43, s69, 0
	s_mov_b32 s50, 1
	v_mov_b32_e32 v16, 0
	s_branch .LBB0_1852

.LBB0_1907:
	s_or_b64 exec, exec, s[6:7]
	s_cmp_lt_i32 s67, 25
	s_cbranch_scc1 .LBB0_1961
	s_waitcnt vmcnt(0)
	v_readlane_b32 s4, v232, 0
	v_readlane_b32 s5, v232, 1
	s_waitcnt vmcnt(0)
	s_barrier
	s_and_saveexec_b64 s[6:7], s[4:5]
	s_cbranch_execz .LBB0_1960
	s_add_i32 s4, 0, 0x20000
	v_mov_b32_e32 v0, s4
	s_waitcnt vmcnt(0) expcnt(0) lgkmcnt(0)
	buffer_wbl2 sc1
	ds_read_b32 v2, v0
	s_add_i32 s4, 0, 0x20004
	v_mov_b32_e32 v0, s4
	ds_read_b32 v0, v0
	s_waitcnt lgkmcnt(1)
	v_cmp_ne_u32_e32 vcc, 0, v2
	s_cbranch_vccnz .LBB0_1924
	s_add_u32 s8, s68, 0x23718200
	s_addc_u32 s9, s69, 0
	s_add_u32 s10, s68, 0x23718400
	s_addc_u32 s11, s69, 0
	s_add_u32 s12, s68, 0x23718500
	s_addc_u32 s13, s69, 0
	s_add_u32 s14, s68, 0x23718600
	s_addc_u32 s15, s69, 0
	s_add_u32 s16, s68, 0x23718700
	s_addc_u32 s17, s69, 0
	s_add_u32 s18, s68, 0x23718800
	s_addc_u32 s19, s69, 0
	s_add_u32 s20, s68, 0x23718900
	s_addc_u32 s21, s69, 0
	s_add_u32 s22, s68, 0x23718a00
	s_addc_u32 s23, s69, 0
	s_add_u32 s24, s68, 0x23718b00
	s_addc_u32 s25, s69, 0
	s_add_u32 s26, s68, 0x23718c00
	s_addc_u32 s27, s69, 0
	s_add_u32 s28, s68, 0x23718d00
	s_addc_u32 s29, s69, 0
	s_add_u32 s30, s68, 0x23718e00
	s_addc_u32 s31, s69, 0
	s_add_u32 s34, s68, 0x23718f00
	s_addc_u32 s35, s69, 0
	s_add_u32 s36, s68, 0x23719000
	s_load_dword s4, s[0:1], 0x110
	s_addc_u32 s37, s69, 0
	s_add_u32 s38, s68, 0x23719100
	s_addc_u32 s39, s69, 0
	s_add_u32 s40, s68, 0x23719200
	s_addc_u32 s41, s69, 0
	s_waitcnt lgkmcnt(0)
	s_mul_i32 s4, s65, s4
	s_add_u32 s42, s68, 0x23719300
	s_mul_i32 s3, s4, s3
	s_addc_u32 s43, s69, 0
	s_mov_b32 s50, 1
	v_mov_b32_e32 v16, 0
	s_branch .LBB0_1912

.LBB0_1982:
	s_cmp_lt_i32 s67, 26
	s_cbranch_scc1 .LBB0_2036
	s_waitcnt vmcnt(0)
	v_readlane_b32 s4, v232, 0
	v_readlane_b32 s5, v232, 1
	s_waitcnt vmcnt(0)
	s_barrier
	s_and_saveexec_b64 s[6:7], s[4:5]
	s_cbranch_execz .LBB0_2035
	s_add_i32 s4, 0, 0x20000
	v_mov_b32_e32 v0, s4
	s_waitcnt vmcnt(0) expcnt(0) lgkmcnt(0)
	buffer_wbl2 sc1
	ds_read_b32 v2, v0
	s_add_i32 s4, 0, 0x20004
	v_mov_b32_e32 v0, s4
	ds_read_b32 v0, v0
	s_waitcnt lgkmcnt(1)
	v_cmp_ne_u32_e32 vcc, 0, v2
	s_cbranch_vccnz .LBB0_1999
	s_add_u32 s8, s68, 0x23718200
	s_addc_u32 s9, s69, 0
	s_add_u32 s10, s68, 0x23718400
	s_addc_u32 s11, s69, 0
	s_add_u32 s12, s68, 0x23718500
	s_addc_u32 s13, s69, 0
	s_add_u32 s14, s68, 0x23718600
	s_addc_u32 s15, s69, 0
	s_add_u32 s16, s68, 0x23718700
	s_addc_u32 s17, s69, 0
	s_add_u32 s18, s68, 0x23718800
	s_addc_u32 s19, s69, 0
	s_add_u32 s20, s68, 0x23718900
	s_addc_u32 s21, s69, 0
	s_add_u32 s22, s68, 0x23718a00
	s_addc_u32 s23, s69, 0
	s_add_u32 s24, s68, 0x23718b00
	s_addc_u32 s25, s69, 0
	s_add_u32 s26, s68, 0x23718c00
	s_addc_u32 s27, s69, 0
	s_add_u32 s28, s68, 0x23718d00
	s_addc_u32 s29, s69, 0
	s_add_u32 s30, s68, 0x23718e00
	s_addc_u32 s31, s69, 0
	s_add_u32 s34, s68, 0x23718f00
	s_addc_u32 s35, s69, 0
	s_add_u32 s36, s68, 0x23719000
	s_load_dword s4, s[0:1], 0x110
	s_addc_u32 s37, s69, 0
	s_add_u32 s38, s68, 0x23719100
	s_addc_u32 s39, s69, 0
	s_add_u32 s40, s68, 0x23719200
	s_addc_u32 s41, s69, 0
	s_waitcnt lgkmcnt(0)
	s_mul_i32 s4, s65, s4
	s_add_u32 s42, s68, 0x23719300
	s_mul_i32 s3, s4, s3
	s_addc_u32 s43, s69, 0
	s_mov_b32 s50, 1
	v_mov_b32_e32 v16, 0
	s_branch .LBB0_1987

.LBB0_2060:
	s_cmp_lt_i32 s67, 27
	s_cbranch_scc1 .LBB0_2114
	s_waitcnt vmcnt(0)
	v_readlane_b32 s4, v232, 0
	v_readlane_b32 s5, v232, 1
	s_waitcnt vmcnt(0)
	s_barrier
	s_and_saveexec_b64 s[6:7], s[4:5]
	s_cbranch_execz .LBB0_2113
	s_add_i32 s3, 0, 0x20000
	v_mov_b32_e32 v0, s3
	s_waitcnt vmcnt(0) expcnt(0) lgkmcnt(0)
	buffer_wbl2 sc1
	ds_read_b32 v2, v0
	s_add_i32 s3, 0, 0x20004
	v_mov_b32_e32 v0, s3
	ds_read_b32 v0, v0
	s_waitcnt lgkmcnt(1)
	v_cmp_ne_u32_e32 vcc, 0, v2
	s_cbranch_vccnz .LBB0_2077
	s_add_u32 s8, s68, 0x23718200
	s_addc_u32 s9, s69, 0
	s_add_u32 s10, s68, 0x23718400
	s_addc_u32 s11, s69, 0
	s_add_u32 s12, s68, 0x23718500
	s_addc_u32 s13, s69, 0
	s_add_u32 s14, s68, 0x23718600
	s_addc_u32 s15, s69, 0
	s_add_u32 s16, s68, 0x23718700
	s_addc_u32 s17, s69, 0
	s_add_u32 s18, s68, 0x23718800
	s_addc_u32 s19, s69, 0
	s_add_u32 s20, s68, 0x23718900
	s_addc_u32 s21, s69, 0
	s_add_u32 s22, s68, 0x23718a00
	s_addc_u32 s23, s69, 0
	s_add_u32 s24, s68, 0x23718b00
	s_addc_u32 s25, s69, 0
	s_add_u32 s26, s68, 0x23718c00
	s_addc_u32 s27, s69, 0
	s_add_u32 s28, s68, 0x23718d00
	s_addc_u32 s29, s69, 0
	s_add_u32 s30, s68, 0x23718e00
	s_addc_u32 s31, s69, 0
	s_add_u32 s34, s68, 0x23718f00
	s_addc_u32 s35, s69, 0
	s_add_u32 s36, s68, 0x23719000
	s_load_dword s3, s[0:1], 0x110
	s_addc_u32 s37, s69, 0
	s_add_u32 s38, s68, 0x23719100
	s_addc_u32 s39, s69, 0
	s_add_u32 s40, s68, 0x23719200
	s_addc_u32 s41, s69, 0
	s_waitcnt lgkmcnt(0)
	s_mul_i32 s3, s65, s3
	s_add_u32 s42, s68, 0x23719300
	s_mul_i32 s3, s3, s64
	s_addc_u32 s43, s69, 0
	s_mov_b32 s50, 1
	v_mov_b32_e32 v16, 0
	s_branch .LBB0_2065

.LBB0_2120:
	s_or_b64 exec, exec, s[6:7]
	s_cmp_lt_i32 s67, 28
	s_cbranch_scc1 .LBB0_2174
	s_waitcnt vmcnt(0)
	v_readlane_b32 s4, v232, 0
	v_readlane_b32 s5, v232, 1
	s_waitcnt vmcnt(0)
	s_barrier
	s_and_saveexec_b64 s[6:7], s[4:5]
	s_cbranch_execz .LBB0_2173
	s_add_i32 s4, 0, 0x20000
	v_mov_b32_e32 v0, s4
	s_waitcnt vmcnt(0) expcnt(0) lgkmcnt(0)
	buffer_wbl2 sc1
	ds_read_b32 v2, v0
	s_add_i32 s4, 0, 0x20004
	v_mov_b32_e32 v0, s4
	ds_read_b32 v0, v0
	s_waitcnt lgkmcnt(1)
	v_cmp_ne_u32_e32 vcc, 0, v2
	s_cbranch_vccnz .LBB0_2137
	s_add_u32 s8, s68, 0x23718200
	s_addc_u32 s9, s69, 0
	s_add_u32 s10, s68, 0x23718400
	s_addc_u32 s11, s69, 0
	s_add_u32 s12, s68, 0x23718500
	s_addc_u32 s13, s69, 0
	s_add_u32 s14, s68, 0x23718600
	s_addc_u32 s15, s69, 0
	s_add_u32 s16, s68, 0x23718700
	s_addc_u32 s17, s69, 0
	s_add_u32 s18, s68, 0x23718800
	s_addc_u32 s19, s69, 0
	s_add_u32 s20, s68, 0x23718900
	s_addc_u32 s21, s69, 0
	s_add_u32 s22, s68, 0x23718a00
	s_addc_u32 s23, s69, 0
	s_add_u32 s24, s68, 0x23718b00
	s_addc_u32 s25, s69, 0
	s_add_u32 s26, s68, 0x23718c00
	s_addc_u32 s27, s69, 0
	s_add_u32 s28, s68, 0x23718d00
	s_addc_u32 s29, s69, 0
	s_add_u32 s30, s68, 0x23718e00
	s_addc_u32 s31, s69, 0
	s_add_u32 s34, s68, 0x23718f00
	s_addc_u32 s35, s69, 0
	s_add_u32 s36, s68, 0x23719000
	s_load_dword s4, s[0:1], 0x110
	s_addc_u32 s37, s69, 0
	s_add_u32 s38, s68, 0x23719100
	s_addc_u32 s39, s69, 0
	s_add_u32 s40, s68, 0x23719200
	s_addc_u32 s41, s69, 0
	s_waitcnt lgkmcnt(0)
	s_mul_i32 s4, s65, s4
	s_add_u32 s42, s68, 0x23719300
	s_mul_i32 s3, s4, s3
	s_addc_u32 s43, s69, 0
	s_mov_b32 s50, 1
	v_mov_b32_e32 v16, 0
	s_branch .LBB0_2125

.LBB0_2215:
	s_cmp_lt_i32 s67, 29
	s_cbranch_scc1 .LBB0_2269
	s_waitcnt vmcnt(0)
	v_readlane_b32 s4, v232, 0
	v_readlane_b32 s5, v232, 1
	s_waitcnt vmcnt(0)
	s_barrier
	s_and_saveexec_b64 s[6:7], s[4:5]
	s_cbranch_execz .LBB0_2268
	s_add_i32 s3, 0, 0x20000
	v_mov_b32_e32 v0, s3
	s_waitcnt vmcnt(0) expcnt(0) lgkmcnt(0)
	buffer_wbl2 sc1
	ds_read_b32 v2, v0
	s_add_i32 s3, 0, 0x20004
	v_mov_b32_e32 v0, s3
	ds_read_b32 v0, v0
	s_waitcnt lgkmcnt(1)
	v_cmp_ne_u32_e32 vcc, 0, v2
	s_cbranch_vccnz .LBB0_2232
	s_add_u32 s8, s68, 0x23718200
	s_addc_u32 s9, s69, 0
	s_add_u32 s10, s68, 0x23718400
	s_addc_u32 s11, s69, 0
	s_add_u32 s12, s68, 0x23718500
	s_addc_u32 s13, s69, 0
	s_add_u32 s14, s68, 0x23718600
	s_addc_u32 s15, s69, 0
	s_add_u32 s16, s68, 0x23718700
	s_addc_u32 s17, s69, 0
	s_add_u32 s18, s68, 0x23718800
	s_addc_u32 s19, s69, 0
	s_add_u32 s20, s68, 0x23718900
	s_addc_u32 s21, s69, 0
	s_add_u32 s22, s68, 0x23718a00
	s_addc_u32 s23, s69, 0
	s_add_u32 s24, s68, 0x23718b00
	s_addc_u32 s25, s69, 0
	s_add_u32 s26, s68, 0x23718c00
	s_addc_u32 s27, s69, 0
	s_add_u32 s28, s68, 0x23718d00
	s_addc_u32 s29, s69, 0
	s_add_u32 s30, s68, 0x23718e00
	s_addc_u32 s31, s69, 0
	s_add_u32 s34, s68, 0x23718f00
	s_addc_u32 s35, s69, 0
	s_add_u32 s36, s68, 0x23719000
	s_load_dword s3, s[0:1], 0x110
	s_addc_u32 s37, s69, 0
	s_add_u32 s38, s68, 0x23719100
	s_addc_u32 s39, s69, 0
	s_add_u32 s40, s68, 0x23719200
	s_addc_u32 s41, s69, 0
	s_waitcnt lgkmcnt(0)
	s_mul_i32 s3, s65, s3
	s_add_u32 s42, s68, 0x23719300
	s_mul_i32 s3, s3, s64
	s_addc_u32 s43, s69, 0
	s_mov_b32 s50, 1
	v_mov_b32_e32 v16, 0
	s_branch .LBB0_2220

.LBB0_2338:
	s_cmp_lt_i32 s67, 30
	s_cbranch_scc1 .LBB0_2392
	s_waitcnt vmcnt(0)
	v_readlane_b32 s4, v232, 0
	v_readlane_b32 s5, v232, 1
	s_waitcnt vmcnt(0) lgkmcnt(0)
	s_barrier
	s_and_saveexec_b64 s[6:7], s[4:5]
	s_cbranch_execz .LBB0_2391
	s_add_i32 s3, 0, 0x20000
	v_mov_b32_e32 v0, s3
	s_waitcnt vmcnt(0) expcnt(0) lgkmcnt(0)
	buffer_wbl2 sc1
	ds_read_b32 v2, v0
	s_add_i32 s3, 0, 0x20004
	v_mov_b32_e32 v0, s3
	ds_read_b32 v0, v0
	s_waitcnt lgkmcnt(1)
	v_cmp_ne_u32_e32 vcc, 0, v2
	s_cbranch_vccnz .LBB0_2355
	s_add_u32 s8, s68, 0x23718200
	s_addc_u32 s9, s69, 0
	s_add_u32 s10, s68, 0x23718400
	s_addc_u32 s11, s69, 0
	s_add_u32 s12, s68, 0x23718500
	s_addc_u32 s13, s69, 0
	s_add_u32 s14, s68, 0x23718600
	s_addc_u32 s15, s69, 0
	s_add_u32 s16, s68, 0x23718700
	s_addc_u32 s17, s69, 0
	s_add_u32 s18, s68, 0x23718800
	s_addc_u32 s19, s69, 0
	s_add_u32 s20, s68, 0x23718900
	s_addc_u32 s21, s69, 0
	s_add_u32 s22, s68, 0x23718a00
	s_addc_u32 s23, s69, 0
	s_add_u32 s24, s68, 0x23718b00
	s_addc_u32 s25, s69, 0
	s_add_u32 s26, s68, 0x23718c00
	s_addc_u32 s27, s69, 0
	s_add_u32 s28, s68, 0x23718d00
	s_addc_u32 s29, s69, 0
	s_add_u32 s30, s68, 0x23718e00
	s_addc_u32 s31, s69, 0
	s_add_u32 s34, s68, 0x23718f00
	s_addc_u32 s35, s69, 0
	s_add_u32 s36, s68, 0x23719000
	s_load_dword s3, s[0:1], 0x110
	s_addc_u32 s37, s69, 0
	s_add_u32 s38, s68, 0x23719100
	s_addc_u32 s39, s69, 0
	s_add_u32 s40, s68, 0x23719200
	s_addc_u32 s41, s69, 0
	s_waitcnt lgkmcnt(0)
	s_mul_i32 s3, s65, s3
	s_add_u32 s42, s68, 0x23719300
	s_mul_i32 s3, s3, s64
	s_addc_u32 s43, s69, 0
	s_mov_b32 s50, 1
	v_mov_b32_e32 v16, 0
	s_branch .LBB0_2343

.LBB0_2409:
	s_cmp_lt_i32 s67, 31
	s_cbranch_scc1 .LBB0_2463
	s_waitcnt vmcnt(0)
	v_readlane_b32 s4, v232, 0
	v_readlane_b32 s5, v232, 1
	s_waitcnt vmcnt(0) lgkmcnt(0)
	s_barrier
	s_and_saveexec_b64 s[6:7], s[4:5]
	s_cbranch_execz .LBB0_2462
	s_add_i32 s3, 0, 0x20000
	v_mov_b32_e32 v0, s3
	s_waitcnt vmcnt(0) expcnt(0) lgkmcnt(0)
	buffer_wbl2 sc1
	ds_read_b32 v2, v0
	s_add_i32 s3, 0, 0x20004
	v_mov_b32_e32 v0, s3
	ds_read_b32 v0, v0
	s_waitcnt lgkmcnt(1)
	v_cmp_ne_u32_e32 vcc, 0, v2
	s_cbranch_vccnz .LBB0_2426
	s_add_u32 s8, s68, 0x23718200
	s_addc_u32 s9, s69, 0
	s_add_u32 s10, s68, 0x23718400
	s_addc_u32 s11, s69, 0
	s_add_u32 s12, s68, 0x23718500
	s_addc_u32 s13, s69, 0
	s_add_u32 s14, s68, 0x23718600
	s_addc_u32 s15, s69, 0
	s_add_u32 s16, s68, 0x23718700
	s_addc_u32 s17, s69, 0
	s_add_u32 s18, s68, 0x23718800
	s_addc_u32 s19, s69, 0
	s_add_u32 s20, s68, 0x23718900
	s_addc_u32 s21, s69, 0
	s_add_u32 s22, s68, 0x23718a00
	s_addc_u32 s23, s69, 0
	s_add_u32 s24, s68, 0x23718b00
	s_addc_u32 s25, s69, 0
	s_add_u32 s26, s68, 0x23718c00
	s_addc_u32 s27, s69, 0
	s_add_u32 s28, s68, 0x23718d00
	s_addc_u32 s29, s69, 0
	s_add_u32 s30, s68, 0x23718e00
	s_addc_u32 s31, s69, 0
	s_add_u32 s34, s68, 0x23718f00
	s_addc_u32 s35, s69, 0
	s_add_u32 s36, s68, 0x23719000
	s_load_dword s3, s[0:1], 0x110
	s_addc_u32 s37, s69, 0
	s_add_u32 s38, s68, 0x23719100
	s_addc_u32 s39, s69, 0
	s_add_u32 s40, s68, 0x23719200
	s_addc_u32 s41, s69, 0
	s_waitcnt lgkmcnt(0)
	s_mul_i32 s3, s65, s3
	s_add_u32 s42, s68, 0x23719300
	s_mul_i32 s3, s3, s64
	s_addc_u32 s43, s69, 0
	s_mov_b32 s50, 1
	v_mov_b32_e32 v16, 0
	s_branch .LBB0_2414

.LBB0_2469:
	s_or_b64 exec, exec, s[6:7]
	s_cmp_lt_i32 s67, 32
	s_cbranch_scc1 .LBB0_2523
	s_waitcnt vmcnt(0)
	v_readlane_b32 s4, v232, 0
	v_readlane_b32 s5, v232, 1
	s_waitcnt vmcnt(0)
	s_barrier
	s_and_saveexec_b64 s[6:7], s[4:5]
	s_cbranch_execz .LBB0_2522
	s_add_i32 s4, 0, 0x20000
	v_mov_b32_e32 v0, s4
	s_waitcnt vmcnt(0) expcnt(0) lgkmcnt(0)
	buffer_wbl2 sc1
	ds_read_b32 v2, v0
	s_add_i32 s4, 0, 0x20004
	v_mov_b32_e32 v0, s4
	ds_read_b32 v0, v0
	s_waitcnt lgkmcnt(1)
	v_cmp_ne_u32_e32 vcc, 0, v2
	s_cbranch_vccnz .LBB0_2486
	s_add_u32 s8, s68, 0x23718200
	s_addc_u32 s9, s69, 0
	s_add_u32 s10, s68, 0x23718400
	s_addc_u32 s11, s69, 0
	s_add_u32 s12, s68, 0x23718500
	s_addc_u32 s13, s69, 0
	s_add_u32 s14, s68, 0x23718600
	s_addc_u32 s15, s69, 0
	s_add_u32 s16, s68, 0x23718700
	s_addc_u32 s17, s69, 0
	s_add_u32 s18, s68, 0x23718800
	s_addc_u32 s19, s69, 0
	s_add_u32 s20, s68, 0x23718900
	s_addc_u32 s21, s69, 0
	s_add_u32 s22, s68, 0x23718a00
	s_addc_u32 s23, s69, 0
	s_add_u32 s24, s68, 0x23718b00
	s_addc_u32 s25, s69, 0
	s_add_u32 s26, s68, 0x23718c00
	s_addc_u32 s27, s69, 0
	s_add_u32 s28, s68, 0x23718d00
	s_addc_u32 s29, s69, 0
	s_add_u32 s30, s68, 0x23718e00
	s_addc_u32 s31, s69, 0
	s_add_u32 s34, s68, 0x23718f00
	s_addc_u32 s35, s69, 0
	s_add_u32 s36, s68, 0x23719000
	s_load_dword s4, s[0:1], 0x110
	s_addc_u32 s37, s69, 0
	s_add_u32 s38, s68, 0x23719100
	s_addc_u32 s39, s69, 0
	s_add_u32 s40, s68, 0x23719200
	s_addc_u32 s41, s69, 0
	s_waitcnt lgkmcnt(0)
	s_mul_i32 s4, s65, s4
	s_add_u32 s42, s68, 0x23719300
	s_mul_i32 s3, s4, s3
	s_addc_u32 s43, s69, 0
	s_mov_b32 s50, 1
	v_mov_b32_e32 v16, 0
	s_branch .LBB0_2474

.LBB0_2540:
	s_cmp_lt_i32 s67, 33
	s_cbranch_scc1 .LBB0_2594
	s_waitcnt vmcnt(0)
	v_readlane_b32 s4, v232, 0
	v_readlane_b32 s5, v232, 1
	s_waitcnt vmcnt(0)
	s_barrier
	s_and_saveexec_b64 s[6:7], s[4:5]
	s_cbranch_execz .LBB0_2593
	s_add_i32 s4, 0, 0x20000
	v_mov_b32_e32 v0, s4
	s_waitcnt vmcnt(0) expcnt(0) lgkmcnt(0)
	buffer_wbl2 sc1
	ds_read_b32 v2, v0
	s_add_i32 s4, 0, 0x20004
	v_mov_b32_e32 v0, s4
	ds_read_b32 v0, v0
	s_waitcnt lgkmcnt(1)
	v_cmp_ne_u32_e32 vcc, 0, v2
	s_cbranch_vccnz .LBB0_2557
	s_add_u32 s8, s68, 0x23718200
	s_addc_u32 s9, s69, 0
	s_add_u32 s10, s68, 0x23718400
	s_addc_u32 s11, s69, 0
	s_add_u32 s12, s68, 0x23718500
	s_addc_u32 s13, s69, 0
	s_add_u32 s14, s68, 0x23718600
	s_addc_u32 s15, s69, 0
	s_add_u32 s16, s68, 0x23718700
	s_addc_u32 s17, s69, 0
	s_add_u32 s18, s68, 0x23718800
	s_addc_u32 s19, s69, 0
	s_add_u32 s20, s68, 0x23718900
	s_addc_u32 s21, s69, 0
	s_add_u32 s22, s68, 0x23718a00
	s_addc_u32 s23, s69, 0
	s_add_u32 s24, s68, 0x23718b00
	s_addc_u32 s25, s69, 0
	s_add_u32 s26, s68, 0x23718c00
	s_addc_u32 s27, s69, 0
	s_add_u32 s28, s68, 0x23718d00
	s_addc_u32 s29, s69, 0
	s_add_u32 s30, s68, 0x23718e00
	s_addc_u32 s31, s69, 0
	s_add_u32 s34, s68, 0x23718f00
	s_addc_u32 s35, s69, 0
	s_add_u32 s36, s68, 0x23719000
	s_load_dword s4, s[0:1], 0x110
	s_addc_u32 s37, s69, 0
	s_add_u32 s38, s68, 0x23719100
	s_addc_u32 s39, s69, 0
	s_add_u32 s40, s68, 0x23719200
	s_addc_u32 s41, s69, 0
	s_waitcnt lgkmcnt(0)
	s_mul_i32 s4, s65, s4
	s_add_u32 s42, s68, 0x23719300
	s_mul_i32 s3, s4, s3
	s_addc_u32 s43, s69, 0
	s_mov_b32 s50, 1
	v_mov_b32_e32 v16, 0
	s_branch .LBB0_2545

.LBB0_2615:
	s_cmp_lt_i32 s67, 34
	s_cbranch_scc1 .LBB0_2669
	s_waitcnt vmcnt(0)
	v_readlane_b32 s4, v232, 0
	v_readlane_b32 s5, v232, 1
	s_waitcnt vmcnt(0) lgkmcnt(0)
	s_barrier
	s_and_saveexec_b64 s[6:7], s[4:5]
	s_cbranch_execz .LBB0_2668
	s_add_i32 s3, 0, 0x20000
	v_mov_b32_e32 v0, s3
	s_waitcnt vmcnt(0) expcnt(0) lgkmcnt(0)
	buffer_wbl2 sc1
	ds_read_b32 v2, v0
	s_add_i32 s3, 0, 0x20004
	v_mov_b32_e32 v0, s3
	ds_read_b32 v0, v0
	s_waitcnt lgkmcnt(1)
	v_cmp_ne_u32_e32 vcc, 0, v2
	s_cbranch_vccnz .LBB0_2632
	s_add_u32 s8, s68, 0x23718200
	s_addc_u32 s9, s69, 0
	s_add_u32 s10, s68, 0x23718400
	s_addc_u32 s11, s69, 0
	s_add_u32 s12, s68, 0x23718500
	s_addc_u32 s13, s69, 0
	s_add_u32 s14, s68, 0x23718600
	s_addc_u32 s15, s69, 0
	s_add_u32 s16, s68, 0x23718700
	s_addc_u32 s17, s69, 0
	s_add_u32 s18, s68, 0x23718800
	s_addc_u32 s19, s69, 0
	s_add_u32 s20, s68, 0x23718900
	s_addc_u32 s21, s69, 0
	s_add_u32 s22, s68, 0x23718a00
	s_addc_u32 s23, s69, 0
	s_add_u32 s24, s68, 0x23718b00
	s_addc_u32 s25, s69, 0
	s_add_u32 s26, s68, 0x23718c00
	s_addc_u32 s27, s69, 0
	s_add_u32 s28, s68, 0x23718d00
	s_addc_u32 s29, s69, 0
	s_add_u32 s30, s68, 0x23718e00
	s_addc_u32 s31, s69, 0
	s_add_u32 s34, s68, 0x23718f00
	s_addc_u32 s35, s69, 0
	s_add_u32 s36, s68, 0x23719000
	s_load_dword s3, s[0:1], 0x110
	s_addc_u32 s37, s69, 0
	s_add_u32 s38, s68, 0x23719100
	s_addc_u32 s39, s69, 0
	s_add_u32 s40, s68, 0x23719200
	s_addc_u32 s41, s69, 0
	s_waitcnt lgkmcnt(0)
	s_mul_i32 s3, s65, s3
	s_add_u32 s42, s68, 0x23719300
	s_mul_i32 s3, s3, s64
	s_addc_u32 s43, s69, 0
	s_mov_b32 s50, 1
	v_mov_b32_e32 v16, 0
	s_branch .LBB0_2620

.LBB0_2675:
	s_or_b64 exec, exec, s[6:7]
	s_cmp_lt_i32 s67, 35
	s_cbranch_scc1 .LBB0_2729
	s_waitcnt vmcnt(0)
	v_readlane_b32 s4, v232, 0
	v_readlane_b32 s5, v232, 1
	s_waitcnt vmcnt(0)
	s_barrier
	s_and_saveexec_b64 s[6:7], s[4:5]
	s_cbranch_execz .LBB0_2728
	s_add_i32 s4, 0, 0x20000
	v_mov_b32_e32 v0, s4
	s_waitcnt vmcnt(0) expcnt(0) lgkmcnt(0)
	buffer_wbl2 sc1
	ds_read_b32 v2, v0
	s_add_i32 s4, 0, 0x20004
	v_mov_b32_e32 v0, s4
	ds_read_b32 v0, v0
	s_waitcnt lgkmcnt(1)
	v_cmp_ne_u32_e32 vcc, 0, v2
	s_cbranch_vccnz .LBB0_2692
	s_add_u32 s8, s68, 0x23718200
	s_addc_u32 s9, s69, 0
	s_add_u32 s10, s68, 0x23718400
	s_addc_u32 s11, s69, 0
	s_add_u32 s12, s68, 0x23718500
	s_addc_u32 s13, s69, 0
	s_add_u32 s14, s68, 0x23718600
	s_addc_u32 s15, s69, 0
	s_add_u32 s16, s68, 0x23718700
	s_addc_u32 s17, s69, 0
	s_add_u32 s18, s68, 0x23718800
	s_addc_u32 s19, s69, 0
	s_add_u32 s20, s68, 0x23718900
	s_addc_u32 s21, s69, 0
	s_add_u32 s22, s68, 0x23718a00
	s_addc_u32 s23, s69, 0
	s_add_u32 s24, s68, 0x23718b00
	s_addc_u32 s25, s69, 0
	s_add_u32 s26, s68, 0x23718c00
	s_addc_u32 s27, s69, 0
	s_add_u32 s28, s68, 0x23718d00
	s_addc_u32 s29, s69, 0
	s_add_u32 s30, s68, 0x23718e00
	s_addc_u32 s31, s69, 0
	s_add_u32 s34, s68, 0x23718f00
	s_addc_u32 s35, s69, 0
	s_add_u32 s36, s68, 0x23719000
	s_load_dword s4, s[0:1], 0x110
	s_addc_u32 s37, s69, 0
	s_add_u32 s38, s68, 0x23719100
	s_addc_u32 s39, s69, 0
	s_add_u32 s40, s68, 0x23719200
	s_addc_u32 s41, s69, 0
	s_waitcnt lgkmcnt(0)
	s_mul_i32 s4, s65, s4
	s_add_u32 s42, s68, 0x23719300
	s_mul_i32 s3, s4, s3
	s_addc_u32 s43, s69, 0
	s_mov_b32 s50, 1
	v_mov_b32_e32 v16, 0
	s_branch .LBB0_2680

.LBB0_2746:
	s_cmp_lt_i32 s67, 36
	s_cbranch_scc1 .LBB0_2800
	s_waitcnt vmcnt(0)
	v_readlane_b32 s4, v232, 0
	v_readlane_b32 s5, v232, 1
	s_waitcnt vmcnt(0)
	s_barrier
	s_and_saveexec_b64 s[6:7], s[4:5]
	s_cbranch_execz .LBB0_2799
	s_add_i32 s4, 0, 0x20000
	v_mov_b32_e32 v0, s4
	s_waitcnt vmcnt(0) expcnt(0) lgkmcnt(0)
	buffer_wbl2 sc1
	ds_read_b32 v2, v0
	s_add_i32 s4, 0, 0x20004
	v_mov_b32_e32 v0, s4
	ds_read_b32 v0, v0
	s_waitcnt lgkmcnt(1)
	v_cmp_ne_u32_e32 vcc, 0, v2
	s_cbranch_vccnz .LBB0_2763
	s_add_u32 s8, s68, 0x23718200
	s_addc_u32 s9, s69, 0
	s_add_u32 s10, s68, 0x23718400
	s_addc_u32 s11, s69, 0
	s_add_u32 s12, s68, 0x23718500
	s_addc_u32 s13, s69, 0
	s_add_u32 s14, s68, 0x23718600
	s_addc_u32 s15, s69, 0
	s_add_u32 s16, s68, 0x23718700
	s_addc_u32 s17, s69, 0
	s_add_u32 s18, s68, 0x23718800
	s_addc_u32 s19, s69, 0
	s_add_u32 s20, s68, 0x23718900
	s_addc_u32 s21, s69, 0
	s_add_u32 s22, s68, 0x23718a00
	s_addc_u32 s23, s69, 0
	s_add_u32 s24, s68, 0x23718b00
	s_addc_u32 s25, s69, 0
	s_add_u32 s26, s68, 0x23718c00
	s_addc_u32 s27, s69, 0
	s_add_u32 s28, s68, 0x23718d00
	s_addc_u32 s29, s69, 0
	s_add_u32 s30, s68, 0x23718e00
	s_addc_u32 s31, s69, 0
	s_add_u32 s34, s68, 0x23718f00
	s_addc_u32 s35, s69, 0
	s_add_u32 s36, s68, 0x23719000
	s_load_dword s4, s[0:1], 0x110
	s_addc_u32 s37, s69, 0
	s_add_u32 s38, s68, 0x23719100
	s_addc_u32 s39, s69, 0
	s_add_u32 s40, s68, 0x23719200
	s_addc_u32 s41, s69, 0
	s_waitcnt lgkmcnt(0)
	s_mul_i32 s4, s65, s4
	s_add_u32 s42, s68, 0x23719300
	s_mul_i32 s3, s4, s3
	s_addc_u32 s43, s69, 0
	s_mov_b32 s50, 1
	v_mov_b32_e32 v16, 0
	s_branch .LBB0_2751

.LBB0_2821:
	s_cmp_lt_i32 s67, 37
	s_cbranch_scc1 .LBB0_2875
	s_waitcnt vmcnt(0)
	v_readlane_b32 s4, v232, 0
	v_readlane_b32 s5, v232, 1
	s_waitcnt vmcnt(0) lgkmcnt(0)
	s_barrier
	s_and_saveexec_b64 s[6:7], s[4:5]
	s_cbranch_execz .LBB0_2874
	s_add_i32 s3, 0, 0x20000
	v_mov_b32_e32 v0, s3
	s_waitcnt vmcnt(0) expcnt(0) lgkmcnt(0)
	buffer_wbl2 sc1
	ds_read_b32 v2, v0
	s_add_i32 s3, 0, 0x20004
	v_mov_b32_e32 v0, s3
	ds_read_b32 v0, v0
	s_waitcnt lgkmcnt(1)
	v_cmp_ne_u32_e32 vcc, 0, v2
	s_cbranch_vccnz .LBB0_2838
	s_add_u32 s8, s68, 0x23718200
	s_addc_u32 s9, s69, 0
	s_add_u32 s10, s68, 0x23718400
	s_addc_u32 s11, s69, 0
	s_add_u32 s12, s68, 0x23718500
	s_addc_u32 s13, s69, 0
	s_add_u32 s14, s68, 0x23718600
	s_addc_u32 s15, s69, 0
	s_add_u32 s16, s68, 0x23718700
	s_addc_u32 s17, s69, 0
	s_add_u32 s18, s68, 0x23718800
	s_addc_u32 s19, s69, 0
	s_add_u32 s20, s68, 0x23718900
	s_addc_u32 s21, s69, 0
	s_add_u32 s22, s68, 0x23718a00
	s_addc_u32 s23, s69, 0
	s_add_u32 s24, s68, 0x23718b00
	s_addc_u32 s25, s69, 0
	s_add_u32 s26, s68, 0x23718c00
	s_addc_u32 s27, s69, 0
	s_add_u32 s28, s68, 0x23718d00
	s_addc_u32 s29, s69, 0
	s_add_u32 s30, s68, 0x23718e00
	s_addc_u32 s31, s69, 0
	s_add_u32 s34, s68, 0x23718f00
	s_addc_u32 s35, s69, 0
	s_add_u32 s36, s68, 0x23719000
	s_load_dword s3, s[0:1], 0x110
	s_addc_u32 s37, s69, 0
	s_add_u32 s38, s68, 0x23719100
	s_addc_u32 s39, s69, 0
	s_add_u32 s40, s68, 0x23719200
	s_addc_u32 s41, s69, 0
	s_waitcnt lgkmcnt(0)
	s_mul_i32 s3, s65, s3
	s_add_u32 s42, s68, 0x23719300
	s_mul_i32 s3, s3, s64
	s_addc_u32 s43, s69, 0
	s_mov_b32 s50, 1
	v_mov_b32_e32 v16, 0
	s_branch .LBB0_2826

.LBB0_2881:
	s_or_b64 exec, exec, s[6:7]
	s_cmp_lt_i32 s67, 38
	s_cbranch_scc1 .LBB0_2935
	s_waitcnt vmcnt(0)
	v_readlane_b32 s4, v232, 0
	v_readlane_b32 s5, v232, 1
	s_waitcnt vmcnt(0)
	s_barrier
	s_and_saveexec_b64 s[6:7], s[4:5]
	s_cbranch_execz .LBB0_2934
	s_add_i32 s4, 0, 0x20000
	v_mov_b32_e32 v0, s4
	s_waitcnt vmcnt(0) expcnt(0) lgkmcnt(0)
	buffer_wbl2 sc1
	ds_read_b32 v2, v0
	s_add_i32 s4, 0, 0x20004
	v_mov_b32_e32 v0, s4
	ds_read_b32 v0, v0
	s_waitcnt lgkmcnt(1)
	v_cmp_ne_u32_e32 vcc, 0, v2
	s_cbranch_vccnz .LBB0_2898
	s_add_u32 s8, s68, 0x23718200
	s_addc_u32 s9, s69, 0
	s_add_u32 s10, s68, 0x23718400
	s_addc_u32 s11, s69, 0
	s_add_u32 s12, s68, 0x23718500
	s_addc_u32 s13, s69, 0
	s_add_u32 s14, s68, 0x23718600
	s_addc_u32 s15, s69, 0
	s_add_u32 s16, s68, 0x23718700
	s_addc_u32 s17, s69, 0
	s_add_u32 s18, s68, 0x23718800
	s_addc_u32 s19, s69, 0
	s_add_u32 s20, s68, 0x23718900
	s_addc_u32 s21, s69, 0
	s_add_u32 s22, s68, 0x23718a00
	s_addc_u32 s23, s69, 0
	s_add_u32 s24, s68, 0x23718b00
	s_addc_u32 s25, s69, 0
	s_add_u32 s26, s68, 0x23718c00
	s_addc_u32 s27, s69, 0
	s_add_u32 s28, s68, 0x23718d00
	s_addc_u32 s29, s69, 0
	s_add_u32 s30, s68, 0x23718e00
	s_addc_u32 s31, s69, 0
	s_add_u32 s34, s68, 0x23718f00
	s_addc_u32 s35, s69, 0
	s_add_u32 s36, s68, 0x23719000
	s_load_dword s4, s[0:1], 0x110
	s_addc_u32 s37, s69, 0
	s_add_u32 s38, s68, 0x23719100
	s_addc_u32 s39, s69, 0
	s_add_u32 s40, s68, 0x23719200
	s_addc_u32 s41, s69, 0
	s_waitcnt lgkmcnt(0)
	s_mul_i32 s4, s65, s4
	s_add_u32 s42, s68, 0x23719300
	s_mul_i32 s3, s4, s3
	s_addc_u32 s43, s69, 0
	s_mov_b32 s50, 1
	v_mov_b32_e32 v16, 0
	s_branch .LBB0_2886

.LBB0_2984:
	s_cmp_lt_i32 s67, 39
	s_cbranch_scc1 .LBB0_3038
	s_waitcnt vmcnt(0)
	v_readlane_b32 s4, v232, 0
	v_readlane_b32 s5, v232, 1
	s_waitcnt vmcnt(0)
	s_barrier
	s_and_saveexec_b64 s[6:7], s[4:5]
	s_cbranch_execz .LBB0_3037
	s_add_i32 s3, 0, 0x20000
	v_mov_b32_e32 v0, s3
	s_waitcnt vmcnt(0) expcnt(0) lgkmcnt(0)
	buffer_wbl2 sc1
	ds_read_b32 v2, v0
	s_add_i32 s3, 0, 0x20004
	v_mov_b32_e32 v0, s3
	ds_read_b32 v0, v0
	s_waitcnt lgkmcnt(1)
	v_cmp_ne_u32_e32 vcc, 0, v2
	s_cbranch_vccnz .LBB0_3001
	s_add_u32 s8, s68, 0x23718200
	s_addc_u32 s9, s69, 0
	s_add_u32 s10, s68, 0x23718400
	s_addc_u32 s11, s69, 0
	s_add_u32 s12, s68, 0x23718500
	s_addc_u32 s13, s69, 0
	s_add_u32 s14, s68, 0x23718600
	s_addc_u32 s15, s69, 0
	s_add_u32 s16, s68, 0x23718700
	s_addc_u32 s17, s69, 0
	s_add_u32 s18, s68, 0x23718800
	s_addc_u32 s19, s69, 0
	s_add_u32 s20, s68, 0x23718900
	s_addc_u32 s21, s69, 0
	s_add_u32 s22, s68, 0x23718a00
	s_addc_u32 s23, s69, 0
	s_add_u32 s24, s68, 0x23718b00
	s_addc_u32 s25, s69, 0
	s_add_u32 s26, s68, 0x23718c00
	s_addc_u32 s27, s69, 0
	s_add_u32 s28, s68, 0x23718d00
	s_addc_u32 s29, s69, 0
	s_add_u32 s30, s68, 0x23718e00
	s_addc_u32 s31, s69, 0
	s_add_u32 s34, s68, 0x23718f00
	s_addc_u32 s35, s69, 0
	s_add_u32 s36, s68, 0x23719000
	s_load_dword s3, s[0:1], 0x110
	s_addc_u32 s37, s69, 0
	s_add_u32 s38, s68, 0x23719100
	s_addc_u32 s39, s69, 0
	s_add_u32 s40, s68, 0x23719200
	s_addc_u32 s41, s69, 0
	s_waitcnt lgkmcnt(0)
	s_mul_i32 s3, s65, s3
	s_add_u32 s42, s68, 0x23719300
	s_mul_i32 s3, s3, s64
	s_addc_u32 s43, s69, 0
	s_mov_b32 s50, 1
	v_mov_b32_e32 v16, 0
	s_branch .LBB0_2989

.LBB0_3042:
	s_or_b64 exec, exec, s[6:7]
	s_cmp_lt_u32 s67, 40
	s_cbranch_scc1 .LBB0_3096
	s_waitcnt vmcnt(0)
	v_readlane_b32 s4, v232, 0
	v_readlane_b32 s5, v232, 1
	s_waitcnt vmcnt(0) lgkmcnt(0)
	s_barrier
	s_and_saveexec_b64 s[6:7], s[4:5]
	s_cbranch_execz .LBB0_3095
	s_add_i32 s3, 0, 0x20000
	v_mov_b32_e32 v0, s3
	s_waitcnt vmcnt(0) expcnt(0) lgkmcnt(0)
	buffer_wbl2 sc1
	ds_read_b32 v2, v0
	s_add_i32 s3, 0, 0x20004
	v_mov_b32_e32 v0, s3
	ds_read_b32 v0, v0
	s_waitcnt lgkmcnt(1)
	v_cmp_ne_u32_e32 vcc, 0, v2
	s_cbranch_vccnz .LBB0_3059
	s_add_u32 s8, s68, 0x23718200
	s_addc_u32 s9, s69, 0
	s_add_u32 s10, s68, 0x23718400
	s_addc_u32 s11, s69, 0
	s_add_u32 s12, s68, 0x23718500
	s_addc_u32 s13, s69, 0
	s_add_u32 s14, s68, 0x23718600
	s_addc_u32 s15, s69, 0
	s_add_u32 s16, s68, 0x23718700
	s_addc_u32 s17, s69, 0
	s_add_u32 s18, s68, 0x23718800
	s_addc_u32 s19, s69, 0
	s_add_u32 s20, s68, 0x23718900
	s_addc_u32 s21, s69, 0
	s_add_u32 s22, s68, 0x23718a00
	s_addc_u32 s23, s69, 0
	s_add_u32 s24, s68, 0x23718b00
	s_addc_u32 s25, s69, 0
	s_add_u32 s26, s68, 0x23718c00
	s_addc_u32 s27, s69, 0
	s_add_u32 s28, s68, 0x23718d00
	s_addc_u32 s29, s69, 0
	s_add_u32 s30, s68, 0x23718e00
	s_addc_u32 s31, s69, 0
	s_add_u32 s34, s68, 0x23718f00
	s_addc_u32 s35, s69, 0
	s_add_u32 s36, s68, 0x23719000
	s_load_dword s3, s[0:1], 0x110
	s_addc_u32 s37, s69, 0
	s_add_u32 s38, s68, 0x23719100
	s_addc_u32 s39, s69, 0
	s_add_u32 s40, s68, 0x23719200
	s_addc_u32 s41, s69, 0
	s_waitcnt lgkmcnt(0)
	s_mul_i32 s3, s65, s3
	s_add_u32 s42, s68, 0x23719300
	s_mul_i32 s3, s3, s64
	s_addc_u32 s43, s69, 0
	s_mov_b32 s50, 1
	v_mov_b32_e32 v16, 0
	s_branch .LBB0_3047

.LBB0_3113:
	s_cmp_lt_i32 s67, 41
	s_cbranch_scc1 .LBB0_3167
	s_waitcnt vmcnt(0)
	v_readlane_b32 s4, v232, 0
	v_readlane_b32 s5, v232, 1
	s_waitcnt vmcnt(0) lgkmcnt(0)
	s_barrier
	s_and_saveexec_b64 s[6:7], s[4:5]
	s_cbranch_execz .LBB0_3166
	s_add_i32 s3, 0, 0x20000
	v_mov_b32_e32 v0, s3
	s_waitcnt vmcnt(0) expcnt(0) lgkmcnt(0)
	buffer_wbl2 sc1
	ds_read_b32 v2, v0
	s_add_i32 s3, 0, 0x20004
	v_mov_b32_e32 v0, s3
	ds_read_b32 v0, v0
	s_waitcnt lgkmcnt(1)
	v_cmp_ne_u32_e32 vcc, 0, v2
	s_cbranch_vccnz .LBB0_3130
	s_add_u32 s8, s68, 0x23718200
	s_addc_u32 s9, s69, 0
	s_add_u32 s10, s68, 0x23718400
	s_addc_u32 s11, s69, 0
	s_add_u32 s12, s68, 0x23718500
	s_addc_u32 s13, s69, 0
	s_add_u32 s14, s68, 0x23718600
	s_addc_u32 s15, s69, 0
	s_add_u32 s16, s68, 0x23718700
	s_addc_u32 s17, s69, 0
	s_add_u32 s18, s68, 0x23718800
	s_addc_u32 s19, s69, 0
	s_add_u32 s20, s68, 0x23718900
	s_addc_u32 s21, s69, 0
	s_add_u32 s22, s68, 0x23718a00
	s_addc_u32 s23, s69, 0
	s_add_u32 s24, s68, 0x23718b00
	s_addc_u32 s25, s69, 0
	s_add_u32 s26, s68, 0x23718c00
	s_addc_u32 s27, s69, 0
	s_add_u32 s28, s68, 0x23718d00
	s_addc_u32 s29, s69, 0
	s_add_u32 s30, s68, 0x23718e00
	s_addc_u32 s31, s69, 0
	s_add_u32 s34, s68, 0x23718f00
	s_addc_u32 s35, s69, 0
	s_add_u32 s36, s68, 0x23719000
	s_load_dword s3, s[0:1], 0x110
	s_addc_u32 s37, s69, 0
	s_add_u32 s38, s68, 0x23719100
	s_addc_u32 s39, s69, 0
	s_add_u32 s40, s68, 0x23719200
	s_addc_u32 s41, s69, 0
	s_waitcnt lgkmcnt(0)
	s_mul_i32 s3, s65, s3
	s_add_u32 s42, s68, 0x23719300
	s_mul_i32 s3, s3, s64
	s_addc_u32 s43, s69, 0
	s_mov_b32 s50, 1
	v_mov_b32_e32 v16, 0
	s_branch .LBB0_3118

.LBB0_3173:
	s_or_b64 exec, exec, s[6:7]
	s_cmp_lt_i32 s67, 42
	s_cbranch_scc1 .LBB0_3227
	s_waitcnt vmcnt(0)
	v_readlane_b32 s4, v232, 0
	v_readlane_b32 s5, v232, 1
	s_waitcnt vmcnt(0)
	s_barrier
	s_and_saveexec_b64 s[6:7], s[4:5]
	s_cbranch_execz .LBB0_3226
	s_add_i32 s4, 0, 0x20000
	v_mov_b32_e32 v0, s4
	s_waitcnt vmcnt(0) expcnt(0) lgkmcnt(0)
	buffer_wbl2 sc1
	ds_read_b32 v2, v0
	s_add_i32 s4, 0, 0x20004
	v_mov_b32_e32 v0, s4
	ds_read_b32 v0, v0
	s_waitcnt lgkmcnt(1)
	v_cmp_ne_u32_e32 vcc, 0, v2
	s_cbranch_vccnz .LBB0_3190
	s_add_u32 s8, s68, 0x23718200
	s_addc_u32 s9, s69, 0
	s_add_u32 s10, s68, 0x23718400
	s_addc_u32 s11, s69, 0
	s_add_u32 s12, s68, 0x23718500
	s_addc_u32 s13, s69, 0
	s_add_u32 s14, s68, 0x23718600
	s_addc_u32 s15, s69, 0
	s_add_u32 s16, s68, 0x23718700
	s_addc_u32 s17, s69, 0
	s_add_u32 s18, s68, 0x23718800
	s_addc_u32 s19, s69, 0
	s_add_u32 s20, s68, 0x23718900
	s_addc_u32 s21, s69, 0
	s_add_u32 s22, s68, 0x23718a00
	s_addc_u32 s23, s69, 0
	s_add_u32 s24, s68, 0x23718b00
	s_addc_u32 s25, s69, 0
	s_add_u32 s26, s68, 0x23718c00
	s_addc_u32 s27, s69, 0
	s_add_u32 s28, s68, 0x23718d00
	s_addc_u32 s29, s69, 0
	s_add_u32 s30, s68, 0x23718e00
	s_addc_u32 s31, s69, 0
	s_add_u32 s34, s68, 0x23718f00
	s_addc_u32 s35, s69, 0
	s_add_u32 s36, s68, 0x23719000
	s_load_dword s4, s[0:1], 0x110
	s_addc_u32 s37, s69, 0
	s_add_u32 s38, s68, 0x23719100
	s_addc_u32 s39, s69, 0
	s_add_u32 s40, s68, 0x23719200
	s_addc_u32 s41, s69, 0
	s_waitcnt lgkmcnt(0)
	s_mul_i32 s4, s65, s4
	s_add_u32 s42, s68, 0x23719300
	s_mul_i32 s3, s4, s3
	s_addc_u32 s43, s69, 0
	s_mov_b32 s50, 1
	v_mov_b32_e32 v16, 0
	s_branch .LBB0_3178

.LBB0_3244:
	s_cmp_lt_i32 s67, 43
	s_cbranch_scc1 .LBB0_3298
	s_waitcnt vmcnt(0)
	s_waitcnt vmcnt(0)
	s_barrier
	s_mov_b64 s[6:7], exec
	v_readlane_b32 s4, v232, 0
	v_readlane_b32 s5, v232, 1
	s_and_b64 s[4:5], s[6:7], s[4:5]
	s_mov_b64 exec, s[4:5]
	s_cbranch_execz .LBB0_3297
	s_add_i32 s4, 0, 0x20000
	v_mov_b32_e32 v0, s4
	s_waitcnt vmcnt(0) expcnt(0) lgkmcnt(0)
	buffer_wbl2 sc1
	ds_read_b32 v2, v0
	s_add_i32 s4, 0, 0x20004
	v_mov_b32_e32 v0, s4
	ds_read_b32 v0, v0
	s_waitcnt lgkmcnt(1)
	v_cmp_ne_u32_e32 vcc, 0, v2
	s_cbranch_vccnz .LBB0_3261
	s_load_dword s4, s[0:1], 0x110
	s_mov_b32 s48, 1
	v_mov_b32_e32 v16, 0
	s_waitcnt lgkmcnt(0)
	s_mul_i32 s4, s65, s4
	s_mul_i32 s3, s4, s3
	s_add_u32 s4, s68, 0x23718200
	s_addc_u32 s5, s69, 0
	s_add_u32 s8, s68, 0x23718400
	s_addc_u32 s9, s69, 0
	s_add_u32 s10, s68, 0x23718500
	s_addc_u32 s11, s69, 0
	s_add_u32 s12, s68, 0x23718600
	s_addc_u32 s13, s69, 0
	s_add_u32 s14, s68, 0x23718700
	s_addc_u32 s15, s69, 0
	s_add_u32 s16, s68, 0x23718800
	s_addc_u32 s17, s69, 0
	s_add_u32 s18, s68, 0x23718900
	s_addc_u32 s19, s69, 0
	s_add_u32 s20, s68, 0x23718a00
	s_addc_u32 s21, s69, 0
	s_add_u32 s22, s68, 0x23718b00
	s_addc_u32 s23, s69, 0
	s_add_u32 s24, s68, 0x23718c00
	s_addc_u32 s25, s69, 0
	s_add_u32 s26, s68, 0x23718d00
	s_addc_u32 s27, s69, 0
	s_add_u32 s28, s68, 0x23718e00
	s_addc_u32 s29, s69, 0
	s_add_u32 s30, s68, 0x23718f00
	s_addc_u32 s31, s69, 0
	s_add_u32 s34, s68, 0x23719000
	s_addc_u32 s35, s69, 0
	s_add_u32 s36, s68, 0x23719100
	s_addc_u32 s37, s69, 0
	s_add_u32 s38, s68, 0x23719200
	s_addc_u32 s39, s69, 0
	s_add_u32 s40, s68, 0x23719300
	s_addc_u32 s41, s69, 0
	s_branch .LBB0_3249
